# K-loop load segments: LDS-DMA loads issued before the ds_reads (same instructions, reordered), on top of v066
# baseline (speedup 1.0000x reference)
; #define PG8_STAGE(bufoff, gbase, voff) do { _Pragma("unroll") for (int _i = 0; _i < 2; ++_i) \
;         __builtin_amdgcn_global_load_lds((const unsigned*)((const char*)(gbase) + (voff)[_i]), (PG8_LAS unsigned*)(lds + (bufoff) + ldsw + _i * 8192), 16, 0, 0); } while (0)
; #define PG8_LDA(dst, b, h) do { _Pragma("unroll") for (int m = 0; m < 4; ++m) _Pragma("unroll") for (int k = 0; k < 2; ++k) dst[m][k] = *(const PG8_LAS bf16x8*)(lds + PG8_SA(b, h) + aoff + m * 2048 + k * 1024); } while (0)
; #define PG8_LDB(dst, b, h) do { _Pragma("unroll") for (int n = 0; n < 2; ++n) _Pragma("unroll") for (int k = 0; k < 2; ++k) dst[n][k] = *(const PG8_LAS bf16x8*)(lds + PG8_SB(b, h) + boff + n * 2048 + k * 1024); } while (0)
; #define PG8_MMA(ai, bj, At, Bt) do { __builtin_amdgcn_s_setprio(1); _Pragma("unroll") for (int m = 0; m < 4; ++m) _Pragma("unroll") for (int n = 0; n < 2; ++n) _Pragma("unroll") for (int k = 0; k < 2; ++k) \
;         acc[ai][bj][m][n] = __builtin_amdgcn_mfma_f32_16x16x32_bf16(Bt[n][k], At[m][k], acc[ai][bj][m][n], 0, 0, 0); __builtin_amdgcn_s_setprio(0); } while (0)
; #define PG8_WAIT_V(n) asm volatile("s_waitcnt vmcnt(" #n ")" ::: "memory")
; #define PG8_WAIT_L(n) asm volatile("s_waitcnt lgkmcnt(" #n ")" ::: "memory")
; #define PG8_BAR __builtin_amdgcn_s_barrier()
; #define PG8_SCHED __builtin_amdgcn_sched_barrier(0)
; template <class Epi, class Sched, bool ALIGN_EPI = false, bool SP2 = false>
; __device__ __forceinline__ void gemm_phase(PG8_LAS unsigned char* lds, const Gemm g, const Sched& S, const Epi& E) {
;     ...
;             PG8_LDB(B0, 0, 0); PG8_LDB(B1, 0, 1); PG8_SCHED; PG8_LDA(At, 0, 0); PG8_STAGE(PG8_SA(1, 1), a1 + hstep, voffA);
;             PG8_WAIT_V(8); PG8_WAIT_L(0); PG8_BAR; PG8_MMA(0, 0, At, B0); PG8_MMA(0, 1, At, B1); PG8_BAR; PG8_SCHED;
;             PG8_LDA(At, 0, 1); PG8_STAGE(PG8_SB(0, 0), b2, voffB); PG8_STAGE(PG8_SB(0, 1), b2 + hstep, voffB); PG8_STAGE(PG8_SA(0, 0), a2, voffA);
;             PG8_WAIT_V(8); PG8_WAIT_L(0); PG8_BAR; PG8_MMA(1, 0, At, B0); PG8_MMA(1, 1, At, B1); PG8_BAR; PG8_SCHED;
.LBB0_180:
	s_add_u32 s36, s34, 0xfff00000
	s_addc_u32 s37, s35, -1
	s_mov_b32 m0, s45
	s_nop 0
	global_load_lds_dwordx4 v138, s[36:37]
	s_mov_b32 m0, s46
	s_nop 0
	global_load_lds_dwordx4 v142, s[36:37]
	s_add_u32 s36, s36, 0x80
	s_addc_u32 s37, s37, 0
	s_cmp_eq_u32 s56, 60
	s_cselect_b32 s39, s7, s37
	s_cselect_b32 s38, s25, s36
	s_cselect_b32 s37, s15, s55
	s_cselect_b32 s36, s31, s54
	s_add_i32 m0, s40, 0xc000
	s_nop 0
	global_load_lds_dwordx4 v148, s[34:35]
	s_add_i32 m0, s40, 0xe000
	s_nop 0
	global_load_lds_dwordx4 v150, s[34:35]
	ds_read_b128 v[130:133], v170
	ds_read_b128 v[134:137], v170 offset:1024
	ds_read_b128 v[178:181], v170 offset:2048
	ds_read_b128 v[182:185], v170 offset:3072
	ds_read_b128 v[186:189], v171
	ds_read_b128 v[190:193], v171 offset:1024
	ds_read_b128 v[194:197], v171 offset:2048
	ds_read_b128 v[200:203], v171 offset:3072
	ds_read_b128 v[204:207], v172
	ds_read_b128 v[208:211], v172 offset:1024
	ds_read_b128 v[212:215], v172 offset:2048
	ds_read_b128 v[216:219], v172 offset:3072
	ds_read_b128 v[220:223], v172 offset:4096
	ds_read_b128 v[224:227], v172 offset:5120
	ds_read_b128 v[228:231], v172 offset:6144
	ds_read_b128 v[232:235], v172 offset:7168
	s_waitcnt vmcnt(8)
	s_waitcnt lgkmcnt(0)
	s_setprio 1
	s_barrier
	v_mfma_f32_16x16x32_bf16 v[126:129], v[130:133], v[204:207], v[126:129]
	v_mfma_f32_16x16x32_bf16 v[122:125], v[178:181], v[204:207], v[122:125]
	v_mfma_f32_16x16x32_bf16 v[110:113], v[130:133], v[212:215], v[110:113]
	v_mfma_f32_16x16x32_bf16 v[106:109], v[178:181], v[212:215], v[106:109]
	v_mfma_f32_16x16x32_bf16 v[94:97], v[130:133], v[220:223], v[94:97]
	v_mfma_f32_16x16x32_bf16 v[90:93], v[178:181], v[220:223], v[90:93]
	v_mfma_f32_16x16x32_bf16 v[78:81], v[130:133], v[228:231], v[78:81]
	v_mfma_f32_16x16x32_bf16 v[74:77], v[178:181], v[228:231], v[74:77]
	v_mfma_f32_16x16x32_bf16 v[126:129], v[134:137], v[208:211], v[126:129]
	v_mfma_f32_16x16x32_bf16 v[122:125], v[182:185], v[208:211], v[122:125]
	v_mfma_f32_16x16x32_bf16 v[110:113], v[134:137], v[216:219], v[110:113]
	v_mfma_f32_16x16x32_bf16 v[106:109], v[182:185], v[216:219], v[106:109]
	v_mfma_f32_16x16x32_bf16 v[94:97], v[134:137], v[224:227], v[94:97]
	v_mfma_f32_16x16x32_bf16 v[90:93], v[182:185], v[224:227], v[90:93]
	v_mfma_f32_16x16x32_bf16 v[78:81], v[134:137], v[232:235], v[78:81]
	v_mfma_f32_16x16x32_bf16 v[74:77], v[182:185], v[232:235], v[74:77]
	v_mfma_f32_16x16x32_bf16 v[118:121], v[186:189], v[204:207], v[118:121]
	v_mfma_f32_16x16x32_bf16 v[114:117], v[194:197], v[204:207], v[114:117]
	v_mfma_f32_16x16x32_bf16 v[102:105], v[186:189], v[212:215], v[102:105]
	v_mfma_f32_16x16x32_bf16 v[98:101], v[194:197], v[212:215], v[98:101]
	v_mfma_f32_16x16x32_bf16 v[86:89], v[186:189], v[220:223], v[86:89]
	v_mfma_f32_16x16x32_bf16 v[82:85], v[194:197], v[220:223], v[82:85]
	v_mfma_f32_16x16x32_bf16 v[70:73], v[186:189], v[228:231], v[70:73]
	v_mfma_f32_16x16x32_bf16 v[66:69], v[194:197], v[228:231], v[66:69]
	v_mfma_f32_16x16x32_bf16 v[118:121], v[190:193], v[208:211], v[118:121]
	v_mfma_f32_16x16x32_bf16 v[114:117], v[200:203], v[208:211], v[114:117]
	v_mfma_f32_16x16x32_bf16 v[102:105], v[190:193], v[216:219], v[102:105]
	v_mfma_f32_16x16x32_bf16 v[98:101], v[200:203], v[216:219], v[98:101]
	v_mfma_f32_16x16x32_bf16 v[86:89], v[190:193], v[224:227], v[86:89]
	v_mfma_f32_16x16x32_bf16 v[82:85], v[200:203], v[224:227], v[82:85]
	v_mfma_f32_16x16x32_bf16 v[70:73], v[190:193], v[232:235], v[70:73]
	v_mfma_f32_16x16x32_bf16 v[66:69], v[200:203], v[232:235], v[66:69]
	s_barrier
	s_setprio 0
	s_add_i32 s57, s49, s33
	s_mov_b32 m0, s57
	s_nop 0
	global_load_lds_dwordx4 v140, s[36:37]
	s_add_i32 m0, s57, 0x2000
	s_add_u32 s58, s36, 0x100000
	s_addc_u32 s59, s37, 0
	s_add_i32 s57, s50, s33
	global_load_lds_dwordx4 v144, s[36:37]
	s_mov_b32 m0, s57
	s_nop 0
	global_load_lds_dwordx4 v140, s[58:59]
	s_add_i32 m0, s57, 0x2000
	s_nop 0
	global_load_lds_dwordx4 v144, s[58:59]
	ds_read_b128 v[204:207], v172 offset:16384
	ds_read_b128 v[208:211], v172 offset:17408
	ds_read_b128 v[212:215], v172 offset:18432
	ds_read_b128 v[216:219], v172 offset:19456
	ds_read_b128 v[220:223], v172 offset:20480
	ds_read_b128 v[224:227], v172 offset:21504
	ds_read_b128 v[228:231], v172 offset:22528
	ds_read_b128 v[232:235], v172 offset:23552
	s_waitcnt vmcnt(6)
	s_waitcnt lgkmcnt(0)
	s_setprio 1
	s_barrier
	v_mfma_f32_16x16x32_bf16 v[62:65], v[130:133], v[204:207], v[62:65]
	v_mfma_f32_16x16x32_bf16 v[58:61], v[178:181], v[204:207], v[58:61]
	v_mfma_f32_16x16x32_bf16 v[46:49], v[130:133], v[212:215], v[46:49]
	v_mfma_f32_16x16x32_bf16 v[42:45], v[178:181], v[212:215], v[42:45]
	v_mfma_f32_16x16x32_bf16 v[30:33], v[130:133], v[220:223], v[30:33]
	v_mfma_f32_16x16x32_bf16 v[26:29], v[178:181], v[220:223], v[26:29]
	v_mfma_f32_16x16x32_bf16 v[14:17], v[130:133], v[228:231], v[14:17]
	v_mfma_f32_16x16x32_bf16 v[10:13], v[178:181], v[228:231], v[10:13]
	v_mfma_f32_16x16x32_bf16 v[62:65], v[134:137], v[208:211], v[62:65]
	v_mfma_f32_16x16x32_bf16 v[58:61], v[182:185], v[208:211], v[58:61]
	v_mfma_f32_16x16x32_bf16 v[46:49], v[134:137], v[216:219], v[46:49]
	v_mfma_f32_16x16x32_bf16 v[42:45], v[182:185], v[216:219], v[42:45]
	v_mfma_f32_16x16x32_bf16 v[30:33], v[134:137], v[224:227], v[30:33]
	v_mfma_f32_16x16x32_bf16 v[26:29], v[182:185], v[224:227], v[26:29]
	v_mfma_f32_16x16x32_bf16 v[14:17], v[134:137], v[232:235], v[14:17]
	v_mfma_f32_16x16x32_bf16 v[10:13], v[182:185], v[232:235], v[10:13]
	v_mfma_f32_16x16x32_bf16 v[54:57], v[186:189], v[204:207], v[54:57]
	v_mfma_f32_16x16x32_bf16 v[50:53], v[194:197], v[204:207], v[50:53]
	v_mfma_f32_16x16x32_bf16 v[38:41], v[186:189], v[212:215], v[38:41]
	v_mfma_f32_16x16x32_bf16 v[34:37], v[194:197], v[212:215], v[34:37]
	v_mfma_f32_16x16x32_bf16 v[22:25], v[186:189], v[220:223], v[22:25]
	v_mfma_f32_16x16x32_bf16 v[18:21], v[194:197], v[220:223], v[18:21]
	v_mfma_f32_16x16x32_bf16 v[6:9], v[186:189], v[228:231], v[6:9]
	v_mfma_f32_16x16x32_bf16 v[2:5], v[194:197], v[228:231], v[2:5]
	v_mfma_f32_16x16x32_bf16 v[54:57], v[190:193], v[208:211], v[54:57]
	v_mfma_f32_16x16x32_bf16 v[50:53], v[200:203], v[208:211], v[50:53]
	v_mfma_f32_16x16x32_bf16 v[38:41], v[190:193], v[216:219], v[38:41]
	v_mfma_f32_16x16x32_bf16 v[34:37], v[200:203], v[216:219], v[34:37]
	v_mfma_f32_16x16x32_bf16 v[22:25], v[190:193], v[224:227], v[22:25]
	v_mfma_f32_16x16x32_bf16 v[18:21], v[200:203], v[224:227], v[18:21]
	v_mfma_f32_16x16x32_bf16 v[6:9], v[190:193], v[232:235], v[6:9]
	v_mfma_f32_16x16x32_bf16 v[2:5], v[200:203], v[232:235], v[2:5]
	s_barrier
; #define PG8_STAGE(bufoff, gbase, voff) do { _Pragma("unroll") for (int _i = 0; _i < 2; ++_i) \
;         __builtin_amdgcn_global_load_lds((const unsigned*)((const char*)(gbase) + (voff)[_i]), (PG8_LAS unsigned*)(lds + (bufoff) + ldsw + _i * 8192), 16, 0, 0); } while (0)
; #define PG8_LDA(dst, b, h) do { _Pragma("unroll") for (int m = 0; m < 4; ++m) _Pragma("unroll") for (int k = 0; k < 2; ++k) dst[m][k] = *(const PG8_LAS bf16x8*)(lds + PG8_SA(b, h) + aoff + m * 2048 + k * 1024); } while (0)
; #define PG8_LDB(dst, b, h) do { _Pragma("unroll") for (int n = 0; n < 2; ++n) _Pragma("unroll") for (int k = 0; k < 2; ++k) dst[n][k] = *(const PG8_LAS bf16x8*)(lds + PG8_SB(b, h) + boff + n * 2048 + k * 1024); } while (0)
; #define PG8_MMA(ai, bj, At, Bt) do { __builtin_amdgcn_s_setprio(1); _Pragma("unroll") for (int m = 0; m < 4; ++m) _Pragma("unroll") for (int n = 0; n < 2; ++n) _Pragma("unroll") for (int k = 0; k < 2; ++k) \
;         acc[ai][bj][m][n] = __builtin_amdgcn_mfma_f32_16x16x32_bf16(Bt[n][k], At[m][k], acc[ai][bj][m][n], 0, 0, 0); __builtin_amdgcn_s_setprio(0); } while (0)
; #define PG8_WAIT_V(n) asm volatile("s_waitcnt vmcnt(" #n ")" ::: "memory")
; #define PG8_WAIT_L(n) asm volatile("s_waitcnt lgkmcnt(" #n ")" ::: "memory")
; #define PG8_BAR __builtin_amdgcn_s_barrier()
; #define PG8_SCHED __builtin_amdgcn_sched_barrier(0)
; template <class Epi, class Sched, bool ALIGN_EPI = false, bool SP2 = false>
; __device__ __forceinline__ void gemm_phase(PG8_LAS unsigned char* lds, const Gemm g, const Sched& S, const Epi& E) {
;     ...
;             PG8_LDB(B0, 1, 0); PG8_LDB(B1, 1, 1); PG8_SCHED; PG8_LDA(At, 1, 0); PG8_STAGE(PG8_SA(0, 1), a2 + hstep, voffA);
;             PG8_WAIT_V(8); PG8_WAIT_L(0); PG8_BAR; PG8_MMA(0, 0, At, B0); PG8_MMA(0, 1, At, B1); PG8_BAR; PG8_SCHED;
;             PG8_LDA(At, 1, 1); PG8_STAGE(PG8_SB(1, 0), b3, voffB); PG8_STAGE(PG8_SB(1, 1), b3 + hstep, voffB); PG8_STAGE(PG8_SA(1, 0), a3, voffA);
;             PG8_WAIT_V(8); PG8_WAIT_L(0); PG8_BAR; PG8_MMA(1, 0, At, B0); PG8_MMA(1, 1, At, B1); PG8_BAR; PG8_SCHED;
;     ...
;         if constexpr (ALIGN_EPI) { if (wr == 0) PG8_BAR; }
	s_setprio 0
	s_mov_b32 m0, s40
	s_nop 0
	global_load_lds_dwordx4 v138, s[38:39]
	s_mov_b32 m0, s41
	s_nop 0
	global_load_lds_dwordx4 v142, s[38:39]
	s_add_i32 s57, 0, 0x18000
	s_add_i32 s58, 0, 0x1c000
	s_add_u32 s38, s38, 0x100000
	s_addc_u32 s39, s39, 0
	s_mov_b32 m0, s42
	s_nop 0
	global_load_lds_dwordx4 v138, s[38:39]
	s_mov_b32 m0, s43
	s_nop 0
	global_load_lds_dwordx4 v142, s[38:39]
	v_add_u32_e32 v146, s57, v159
	ds_read_b128 v[130:133], v146
	ds_read_b128 v[134:137], v146 offset:1024
	ds_read_b128 v[178:181], v146 offset:2048
	ds_read_b128 v[182:185], v146 offset:3072
	v_add_u32_e32 v146, s58, v159
	ds_read_b128 v[186:189], v146
	ds_read_b128 v[190:193], v146 offset:1024
	ds_read_b128 v[194:197], v146 offset:2048
	ds_read_b128 v[200:203], v146 offset:3072
	ds_read_b128 v[204:207], v172 offset:32768
	ds_read_b128 v[208:211], v172 offset:33792
	ds_read_b128 v[212:215], v172 offset:34816
	ds_read_b128 v[216:219], v172 offset:35840
	ds_read_b128 v[220:223], v172 offset:36864
	ds_read_b128 v[224:227], v172 offset:37888
	ds_read_b128 v[228:231], v172 offset:38912
	ds_read_b128 v[232:235], v172 offset:39936
	s_waitcnt vmcnt(8)
	s_waitcnt lgkmcnt(0)
	s_setprio 1
	s_barrier
	v_mfma_f32_16x16x32_bf16 v[126:129], v[130:133], v[204:207], v[126:129]
	v_mfma_f32_16x16x32_bf16 v[122:125], v[178:181], v[204:207], v[122:125]
	v_mfma_f32_16x16x32_bf16 v[110:113], v[130:133], v[212:215], v[110:113]
	v_mfma_f32_16x16x32_bf16 v[106:109], v[178:181], v[212:215], v[106:109]
	v_mfma_f32_16x16x32_bf16 v[94:97], v[130:133], v[220:223], v[94:97]
	v_mfma_f32_16x16x32_bf16 v[90:93], v[178:181], v[220:223], v[90:93]
	v_mfma_f32_16x16x32_bf16 v[78:81], v[130:133], v[228:231], v[78:81]
	v_mfma_f32_16x16x32_bf16 v[74:77], v[178:181], v[228:231], v[74:77]
	v_mfma_f32_16x16x32_bf16 v[126:129], v[134:137], v[208:211], v[126:129]
	v_mfma_f32_16x16x32_bf16 v[122:125], v[182:185], v[208:211], v[122:125]
	v_mfma_f32_16x16x32_bf16 v[110:113], v[134:137], v[216:219], v[110:113]
	v_mfma_f32_16x16x32_bf16 v[106:109], v[182:185], v[216:219], v[106:109]
	v_mfma_f32_16x16x32_bf16 v[94:97], v[134:137], v[224:227], v[94:97]
	v_mfma_f32_16x16x32_bf16 v[90:93], v[182:185], v[224:227], v[90:93]
	v_mfma_f32_16x16x32_bf16 v[78:81], v[134:137], v[232:235], v[78:81]
	v_mfma_f32_16x16x32_bf16 v[74:77], v[182:185], v[232:235], v[74:77]
	v_mfma_f32_16x16x32_bf16 v[118:121], v[186:189], v[204:207], v[118:121]
	v_mfma_f32_16x16x32_bf16 v[114:117], v[194:197], v[204:207], v[114:117]
	v_mfma_f32_16x16x32_bf16 v[102:105], v[186:189], v[212:215], v[102:105]
	v_mfma_f32_16x16x32_bf16 v[98:101], v[194:197], v[212:215], v[98:101]
	v_mfma_f32_16x16x32_bf16 v[86:89], v[186:189], v[220:223], v[86:89]
	v_mfma_f32_16x16x32_bf16 v[82:85], v[194:197], v[220:223], v[82:85]
	v_mfma_f32_16x16x32_bf16 v[70:73], v[186:189], v[228:231], v[70:73]
	v_mfma_f32_16x16x32_bf16 v[66:69], v[194:197], v[228:231], v[66:69]
	v_mfma_f32_16x16x32_bf16 v[118:121], v[190:193], v[208:211], v[118:121]
	v_mfma_f32_16x16x32_bf16 v[114:117], v[200:203], v[208:211], v[114:117]
	v_mfma_f32_16x16x32_bf16 v[102:105], v[190:193], v[216:219], v[102:105]
	v_mfma_f32_16x16x32_bf16 v[98:101], v[200:203], v[216:219], v[98:101]
	v_mfma_f32_16x16x32_bf16 v[86:89], v[190:193], v[224:227], v[86:89]
	v_mfma_f32_16x16x32_bf16 v[82:85], v[200:203], v[224:227], v[82:85]
	v_mfma_f32_16x16x32_bf16 v[70:73], v[190:193], v[232:235], v[70:73]
	v_mfma_f32_16x16x32_bf16 v[66:69], v[200:203], v[232:235], v[66:69]
	s_barrier
	s_setprio 0
	s_add_i32 s38, s57, s33
	s_add_u32 s36, s36, 0x80
	s_addc_u32 s37, s37, 0
	s_mov_b32 m0, s38
	s_nop 0
	global_load_lds_dwordx4 v140, s[36:37]
	s_add_i32 m0, s38, 0x2000
	s_add_i32 s38, s58, s33
	global_load_lds_dwordx4 v144, s[36:37]
	s_add_u32 s36, s36, 0x100000
	s_addc_u32 s37, s37, 0
	s_mov_b32 m0, s38
	s_nop 0
	global_load_lds_dwordx4 v140, s[36:37]
	s_add_i32 m0, s38, 0x2000
	s_nop 0
	global_load_lds_dwordx4 v144, s[36:37]
	ds_read_b128 v[204:207], v172 offset:49152
	ds_read_b128 v[208:211], v172 offset:50176
	ds_read_b128 v[212:215], v172 offset:51200
	ds_read_b128 v[216:219], v172 offset:52224
	ds_read_b128 v[220:223], v172 offset:53248
	ds_read_b128 v[224:227], v172 offset:54272
	ds_read_b128 v[228:231], v172 offset:55296
	ds_read_b128 v[232:235], v172 offset:56320
	s_waitcnt vmcnt(6)
	s_waitcnt lgkmcnt(0)
	s_setprio 1
	s_barrier
	v_mfma_f32_16x16x32_bf16 v[62:65], v[130:133], v[204:207], v[62:65]
	v_mfma_f32_16x16x32_bf16 v[58:61], v[178:181], v[204:207], v[58:61]
	v_mfma_f32_16x16x32_bf16 v[46:49], v[130:133], v[212:215], v[46:49]
	v_mfma_f32_16x16x32_bf16 v[42:45], v[178:181], v[212:215], v[42:45]
	v_mfma_f32_16x16x32_bf16 v[30:33], v[130:133], v[220:223], v[30:33]
	v_mfma_f32_16x16x32_bf16 v[26:29], v[178:181], v[220:223], v[26:29]
	v_mfma_f32_16x16x32_bf16 v[14:17], v[130:133], v[228:231], v[14:17]
	v_mfma_f32_16x16x32_bf16 v[10:13], v[178:181], v[228:231], v[10:13]
	v_mfma_f32_16x16x32_bf16 v[62:65], v[134:137], v[208:211], v[62:65]
	v_mfma_f32_16x16x32_bf16 v[58:61], v[182:185], v[208:211], v[58:61]
	v_mfma_f32_16x16x32_bf16 v[46:49], v[134:137], v[216:219], v[46:49]
	v_mfma_f32_16x16x32_bf16 v[42:45], v[182:185], v[216:219], v[42:45]
	v_mfma_f32_16x16x32_bf16 v[30:33], v[134:137], v[224:227], v[30:33]
	v_mfma_f32_16x16x32_bf16 v[26:29], v[182:185], v[224:227], v[26:29]
	v_mfma_f32_16x16x32_bf16 v[14:17], v[134:137], v[232:235], v[14:17]
	v_mfma_f32_16x16x32_bf16 v[10:13], v[182:185], v[232:235], v[10:13]
	v_mfma_f32_16x16x32_bf16 v[54:57], v[186:189], v[204:207], v[54:57]
	v_mfma_f32_16x16x32_bf16 v[50:53], v[194:197], v[204:207], v[50:53]
	v_mfma_f32_16x16x32_bf16 v[38:41], v[186:189], v[212:215], v[38:41]
	v_mfma_f32_16x16x32_bf16 v[34:37], v[194:197], v[212:215], v[34:37]
	v_mfma_f32_16x16x32_bf16 v[22:25], v[186:189], v[220:223], v[22:25]
	v_mfma_f32_16x16x32_bf16 v[18:21], v[194:197], v[220:223], v[18:21]
	v_mfma_f32_16x16x32_bf16 v[6:9], v[186:189], v[228:231], v[6:9]
	v_mfma_f32_16x16x32_bf16 v[2:5], v[194:197], v[228:231], v[2:5]
	v_mfma_f32_16x16x32_bf16 v[54:57], v[190:193], v[208:211], v[54:57]
	v_mfma_f32_16x16x32_bf16 v[50:53], v[200:203], v[208:211], v[50:53]
	v_mfma_f32_16x16x32_bf16 v[38:41], v[190:193], v[216:219], v[38:41]
	v_mfma_f32_16x16x32_bf16 v[34:37], v[200:203], v[216:219], v[34:37]
	v_mfma_f32_16x16x32_bf16 v[22:25], v[190:193], v[224:227], v[22:25]
	v_mfma_f32_16x16x32_bf16 v[18:21], v[200:203], v[224:227], v[18:21]
	v_mfma_f32_16x16x32_bf16 v[6:9], v[190:193], v[232:235], v[6:9]
	v_mfma_f32_16x16x32_bf16 v[2:5], v[200:203], v[232:235], v[2:5]
	s_barrier
	s_setprio 0
	s_add_i32 s56, s56, 2
	s_add_u32 s34, s34, 0x100
	s_addc_u32 s35, s35, 0
	s_add_u32 s54, s54, 0x100
	s_addc_u32 s55, s55, 0
	s_cmp_gt_u32 s56, 61
	s_cbranch_scc0 .LBB0_180
	s_and_b64 vcc, exec, s[12:13]
	s_cbranch_vccz .LBB0_183
	s_barrier

; #define PG8_STAGE(bufoff, gbase, voff) do { _Pragma("unroll") for (int _i = 0; _i < 2; ++_i) \
;         __builtin_amdgcn_global_load_lds((const unsigned*)((const char*)(gbase) + (voff)[_i]), (PG8_LAS unsigned*)(lds + (bufoff) + ldsw + _i * 8192), 16, 0, 0); } while (0)
; #define PG8_LDA(dst, b, h) do { _Pragma("unroll") for (int m = 0; m < 4; ++m) _Pragma("unroll") for (int k = 0; k < 2; ++k) dst[m][k] = *(const PG8_LAS bf16x8*)(lds + PG8_SA(b, h) + aoff + m * 2048 + k * 1024); } while (0)
; #define PG8_LDB(dst, b, h) do { _Pragma("unroll") for (int n = 0; n < 2; ++n) _Pragma("unroll") for (int k = 0; k < 2; ++k) dst[n][k] = *(const PG8_LAS bf16x8*)(lds + PG8_SB(b, h) + boff + n * 2048 + k * 1024); } while (0)
; #define PG8_MMA(ai, bj, At, Bt) do { __builtin_amdgcn_s_setprio(1); _Pragma("unroll") for (int m = 0; m < 4; ++m) _Pragma("unroll") for (int n = 0; n < 2; ++n) _Pragma("unroll") for (int k = 0; k < 2; ++k) \
;         acc[ai][bj][m][n] = __builtin_amdgcn_mfma_f32_16x16x32_bf16(Bt[n][k], At[m][k], acc[ai][bj][m][n], 0, 0, 0); __builtin_amdgcn_s_setprio(0); } while (0)
; #define PG8_WAIT_V(n) asm volatile("s_waitcnt vmcnt(" #n ")" ::: "memory")
; #define PG8_WAIT_L(n) asm volatile("s_waitcnt lgkmcnt(" #n ")" ::: "memory")
; #define PG8_BAR __builtin_amdgcn_s_barrier()
; #define PG8_SCHED __builtin_amdgcn_sched_barrier(0)
; template <class Epi, class Sched, bool ALIGN_EPI = false, bool SP2 = false>
; __device__ __forceinline__ void gemm_phase(PG8_LAS unsigned char* lds, const Gemm g, const Sched& S, const Epi& E) {
;     ...
;             PG8_LDB(B0, 0, 0); PG8_LDB(B1, 0, 1); PG8_SCHED; PG8_LDA(At, 0, 0); PG8_STAGE(PG8_SA(1, 1), a1 + hstep, voffA);
;             PG8_WAIT_V(8); PG8_WAIT_L(0); PG8_BAR; PG8_MMA(0, 0, At, B0); PG8_MMA(0, 1, At, B1); PG8_BAR; PG8_SCHED;
;             PG8_LDA(At, 0, 1); PG8_STAGE(PG8_SB(0, 0), b2, voffB); PG8_STAGE(PG8_SB(0, 1), b2 + hstep, voffB); PG8_STAGE(PG8_SA(0, 0), a2, voffA);
;             PG8_WAIT_V(8); PG8_WAIT_L(0); PG8_BAR; PG8_MMA(1, 0, At, B0); PG8_MMA(1, 1, At, B1); PG8_BAR; PG8_SCHED;
.LBB0_857:
	s_add_u32 s34, s30, 0xfff80000
	s_addc_u32 s35, s31, -1
	s_mov_b32 m0, s43
	s_nop 0
	global_load_lds_dwordx4 v150, s[34:35]
	s_mov_b32 m0, s44
	s_nop 0
	global_load_lds_dwordx4 v154, s[34:35]
	s_add_u32 s34, s34, 0x80
	s_addc_u32 s35, s35, 0
	s_cmp_eq_u32 s56, 28
	s_cselect_b32 s37, s15, s35
	s_cselect_b32 s36, s50, s34
	s_cselect_b32 s35, s13, s53
	s_cselect_b32 s34, s51, s52
	s_add_i32 m0, s29, 0xc000
	s_nop 0
	global_load_lds_dwordx4 v158, s[30:31]
	s_add_i32 m0, s29, 0xe000
	s_nop 0
	global_load_lds_dwordx4 v160, s[30:31]
	ds_read_b128 v[130:133], v180
	ds_read_b128 v[134:137], v180 offset:1024
	ds_read_b128 v[138:141], v180 offset:2048
	ds_read_b128 v[142:145], v180 offset:3072
	ds_read_b128 v[146:149], v181
	ds_read_b128 v[166:169], v181 offset:1024
	ds_read_b128 v[170:173], v181 offset:2048
	ds_read_b128 v[174:177], v181 offset:3072
	ds_read_b128 v[184:187], v182
	ds_read_b128 v[188:191], v182 offset:1024
	ds_read_b128 v[192:195], v182 offset:2048
	ds_read_b128 v[200:203], v182 offset:3072
	ds_read_b128 v[204:207], v182 offset:4096
	ds_read_b128 v[208:211], v182 offset:5120
	ds_read_b128 v[212:215], v182 offset:6144
	ds_read_b128 v[216:219], v182 offset:7168
	s_waitcnt vmcnt(8)
	s_waitcnt lgkmcnt(0)
	s_setprio 1
	s_barrier
	v_mfma_f32_16x16x32_bf16 v[126:129], v[130:133], v[184:187], v[126:129]
	v_mfma_f32_16x16x32_bf16 v[122:125], v[138:141], v[184:187], v[122:125]
	v_mfma_f32_16x16x32_bf16 v[110:113], v[130:133], v[192:195], v[110:113]
	v_mfma_f32_16x16x32_bf16 v[106:109], v[138:141], v[192:195], v[106:109]
	v_mfma_f32_16x16x32_bf16 v[94:97], v[130:133], v[204:207], v[94:97]
	v_mfma_f32_16x16x32_bf16 v[90:93], v[138:141], v[204:207], v[90:93]
	v_mfma_f32_16x16x32_bf16 v[78:81], v[130:133], v[212:215], v[78:81]
	v_mfma_f32_16x16x32_bf16 v[74:77], v[138:141], v[212:215], v[74:77]
	v_mfma_f32_16x16x32_bf16 v[126:129], v[134:137], v[188:191], v[126:129]
	v_mfma_f32_16x16x32_bf16 v[122:125], v[142:145], v[188:191], v[122:125]
	v_mfma_f32_16x16x32_bf16 v[110:113], v[134:137], v[200:203], v[110:113]
	v_mfma_f32_16x16x32_bf16 v[106:109], v[142:145], v[200:203], v[106:109]
	v_mfma_f32_16x16x32_bf16 v[94:97], v[134:137], v[208:211], v[94:97]
	v_mfma_f32_16x16x32_bf16 v[90:93], v[142:145], v[208:211], v[90:93]
	v_mfma_f32_16x16x32_bf16 v[78:81], v[134:137], v[216:219], v[78:81]
	v_mfma_f32_16x16x32_bf16 v[74:77], v[142:145], v[216:219], v[74:77]
	v_mfma_f32_16x16x32_bf16 v[118:121], v[146:149], v[184:187], v[118:121]
	v_mfma_f32_16x16x32_bf16 v[114:117], v[170:173], v[184:187], v[114:117]
	v_mfma_f32_16x16x32_bf16 v[102:105], v[146:149], v[192:195], v[102:105]
	v_mfma_f32_16x16x32_bf16 v[98:101], v[170:173], v[192:195], v[98:101]
	v_mfma_f32_16x16x32_bf16 v[86:89], v[146:149], v[204:207], v[86:89]
	v_mfma_f32_16x16x32_bf16 v[82:85], v[170:173], v[204:207], v[82:85]
	v_mfma_f32_16x16x32_bf16 v[70:73], v[146:149], v[212:215], v[70:73]
	v_mfma_f32_16x16x32_bf16 v[66:69], v[170:173], v[212:215], v[66:69]
	v_mfma_f32_16x16x32_bf16 v[118:121], v[166:169], v[188:191], v[118:121]
	v_mfma_f32_16x16x32_bf16 v[114:117], v[174:177], v[188:191], v[114:117]
	v_mfma_f32_16x16x32_bf16 v[102:105], v[166:169], v[200:203], v[102:105]
	v_mfma_f32_16x16x32_bf16 v[98:101], v[174:177], v[200:203], v[98:101]
	v_mfma_f32_16x16x32_bf16 v[86:89], v[166:169], v[208:211], v[86:89]
	v_mfma_f32_16x16x32_bf16 v[82:85], v[174:177], v[208:211], v[82:85]
	v_mfma_f32_16x16x32_bf16 v[70:73], v[166:169], v[216:219], v[70:73]
	v_mfma_f32_16x16x32_bf16 v[66:69], v[174:177], v[216:219], v[66:69]
	s_barrier
	s_setprio 0
	s_add_i32 s57, s46, s38
	s_mov_b32 m0, s57
	s_nop 0
	global_load_lds_dwordx4 v152, s[34:35]
	s_add_i32 m0, s57, 0x2000
	s_add_u32 s58, s34, 0x80000
	s_addc_u32 s59, s35, 0
	s_add_i32 s57, s47, s38
	global_load_lds_dwordx4 v156, s[34:35]
	s_mov_b32 m0, s57
	s_nop 0
	global_load_lds_dwordx4 v152, s[58:59]
	s_add_i32 m0, s57, 0x2000
	s_nop 0
	global_load_lds_dwordx4 v156, s[58:59]
	ds_read_b128 v[184:187], v182 offset:16384
	ds_read_b128 v[188:191], v182 offset:17408
	ds_read_b128 v[192:195], v182 offset:18432
	ds_read_b128 v[200:203], v182 offset:19456
	ds_read_b128 v[204:207], v182 offset:20480
	ds_read_b128 v[208:211], v182 offset:21504
	ds_read_b128 v[212:215], v182 offset:22528
	ds_read_b128 v[216:219], v182 offset:23552
	s_waitcnt vmcnt(6)
	s_waitcnt lgkmcnt(0)
	s_setprio 1
	s_barrier
	v_mfma_f32_16x16x32_bf16 v[62:65], v[130:133], v[184:187], v[62:65]
	v_mfma_f32_16x16x32_bf16 v[58:61], v[138:141], v[184:187], v[58:61]
	v_mfma_f32_16x16x32_bf16 v[46:49], v[130:133], v[192:195], v[46:49]
	v_mfma_f32_16x16x32_bf16 v[42:45], v[138:141], v[192:195], v[42:45]
	v_mfma_f32_16x16x32_bf16 v[30:33], v[130:133], v[204:207], v[30:33]
	v_mfma_f32_16x16x32_bf16 v[26:29], v[138:141], v[204:207], v[26:29]
	v_mfma_f32_16x16x32_bf16 v[14:17], v[130:133], v[212:215], v[14:17]
	v_mfma_f32_16x16x32_bf16 v[10:13], v[138:141], v[212:215], v[10:13]
	v_mfma_f32_16x16x32_bf16 v[62:65], v[134:137], v[188:191], v[62:65]
	v_mfma_f32_16x16x32_bf16 v[58:61], v[142:145], v[188:191], v[58:61]
	v_mfma_f32_16x16x32_bf16 v[46:49], v[134:137], v[200:203], v[46:49]
	v_mfma_f32_16x16x32_bf16 v[42:45], v[142:145], v[200:203], v[42:45]
	v_mfma_f32_16x16x32_bf16 v[30:33], v[134:137], v[208:211], v[30:33]
	v_mfma_f32_16x16x32_bf16 v[26:29], v[142:145], v[208:211], v[26:29]
	v_mfma_f32_16x16x32_bf16 v[14:17], v[134:137], v[216:219], v[14:17]
	v_mfma_f32_16x16x32_bf16 v[10:13], v[142:145], v[216:219], v[10:13]
	v_mfma_f32_16x16x32_bf16 v[54:57], v[146:149], v[184:187], v[54:57]
	v_mfma_f32_16x16x32_bf16 v[50:53], v[170:173], v[184:187], v[50:53]
	v_mfma_f32_16x16x32_bf16 v[38:41], v[146:149], v[192:195], v[38:41]
	v_mfma_f32_16x16x32_bf16 v[34:37], v[170:173], v[192:195], v[34:37]
	v_mfma_f32_16x16x32_bf16 v[22:25], v[146:149], v[204:207], v[22:25]
	v_mfma_f32_16x16x32_bf16 v[18:21], v[170:173], v[204:207], v[18:21]
	v_mfma_f32_16x16x32_bf16 v[6:9], v[146:149], v[212:215], v[6:9]
	v_mfma_f32_16x16x32_bf16 v[2:5], v[170:173], v[212:215], v[2:5]
	v_mfma_f32_16x16x32_bf16 v[54:57], v[166:169], v[188:191], v[54:57]
	v_mfma_f32_16x16x32_bf16 v[50:53], v[174:177], v[188:191], v[50:53]
	v_mfma_f32_16x16x32_bf16 v[38:41], v[166:169], v[200:203], v[38:41]
	v_mfma_f32_16x16x32_bf16 v[34:37], v[174:177], v[200:203], v[34:37]
	v_mfma_f32_16x16x32_bf16 v[22:25], v[166:169], v[208:211], v[22:25]
	v_mfma_f32_16x16x32_bf16 v[18:21], v[174:177], v[208:211], v[18:21]
	v_mfma_f32_16x16x32_bf16 v[6:9], v[166:169], v[216:219], v[6:9]
	v_mfma_f32_16x16x32_bf16 v[2:5], v[174:177], v[216:219], v[2:5]
	s_barrier
; #define PG8_STAGE(bufoff, gbase, voff) do { _Pragma("unroll") for (int _i = 0; _i < 2; ++_i) \
;         __builtin_amdgcn_global_load_lds((const unsigned*)((const char*)(gbase) + (voff)[_i]), (PG8_LAS unsigned*)(lds + (bufoff) + ldsw + _i * 8192), 16, 0, 0); } while (0)
; #define PG8_LDA(dst, b, h) do { _Pragma("unroll") for (int m = 0; m < 4; ++m) _Pragma("unroll") for (int k = 0; k < 2; ++k) dst[m][k] = *(const PG8_LAS bf16x8*)(lds + PG8_SA(b, h) + aoff + m * 2048 + k * 1024); } while (0)
; #define PG8_LDB(dst, b, h) do { _Pragma("unroll") for (int n = 0; n < 2; ++n) _Pragma("unroll") for (int k = 0; k < 2; ++k) dst[n][k] = *(const PG8_LAS bf16x8*)(lds + PG8_SB(b, h) + boff + n * 2048 + k * 1024); } while (0)
; #define PG8_MMA(ai, bj, At, Bt) do { __builtin_amdgcn_s_setprio(1); _Pragma("unroll") for (int m = 0; m < 4; ++m) _Pragma("unroll") for (int n = 0; n < 2; ++n) _Pragma("unroll") for (int k = 0; k < 2; ++k) \
;         acc[ai][bj][m][n] = __builtin_amdgcn_mfma_f32_16x16x32_bf16(Bt[n][k], At[m][k], acc[ai][bj][m][n], 0, 0, 0); __builtin_amdgcn_s_setprio(0); } while (0)
; #define PG8_WAIT_V(n) asm volatile("s_waitcnt vmcnt(" #n ")" ::: "memory")
; #define PG8_WAIT_L(n) asm volatile("s_waitcnt lgkmcnt(" #n ")" ::: "memory")
; #define PG8_BAR __builtin_amdgcn_s_barrier()
; #define PG8_SCHED __builtin_amdgcn_sched_barrier(0)
; template <class Epi, class Sched, bool ALIGN_EPI = false, bool SP2 = false>
; __device__ __forceinline__ void gemm_phase(PG8_LAS unsigned char* lds, const Gemm g, const Sched& S, const Epi& E) {
;     ...
;             PG8_LDB(B0, 1, 0); PG8_LDB(B1, 1, 1); PG8_SCHED; PG8_LDA(At, 1, 0); PG8_STAGE(PG8_SA(0, 1), a2 + hstep, voffA);
;             PG8_WAIT_V(8); PG8_WAIT_L(0); PG8_BAR; PG8_MMA(0, 0, At, B0); PG8_MMA(0, 1, At, B1); PG8_BAR; PG8_SCHED;
;             PG8_LDA(At, 1, 1); PG8_STAGE(PG8_SB(1, 0), b3, voffB); PG8_STAGE(PG8_SB(1, 1), b3 + hstep, voffB); PG8_STAGE(PG8_SA(1, 0), a3, voffA);
;             PG8_WAIT_V(8); PG8_WAIT_L(0); PG8_BAR; PG8_MMA(1, 0, At, B0); PG8_MMA(1, 1, At, B1); PG8_BAR; PG8_SCHED;
;     ...
;         if constexpr (ALIGN_EPI) { if (wr == 0) PG8_BAR; }
	s_setprio 0
	s_mov_b32 m0, s29
	s_nop 0
	global_load_lds_dwordx4 v150, s[36:37]
	s_mov_b32 m0, s39
	s_nop 0
	global_load_lds_dwordx4 v154, s[36:37]
	s_add_i32 s57, 0, 0x18000
	s_add_i32 s58, 0, 0x1c000
	s_add_u32 s36, s36, 0x80000
	s_addc_u32 s37, s37, 0
	s_mov_b32 m0, s40
	s_nop 0
	global_load_lds_dwordx4 v150, s[36:37]
	s_mov_b32 m0, s41
	s_nop 0
	global_load_lds_dwordx4 v154, s[36:37]
	v_add_u32_e32 v142, s57, v178
	v_add_u32_e32 v174, s58, v178
	ds_read_b128 v[130:133], v142
	ds_read_b128 v[134:137], v142 offset:1024
	ds_read_b128 v[138:141], v142 offset:2048
	ds_read_b128 v[142:145], v142 offset:3072
	ds_read_b128 v[146:149], v174
	ds_read_b128 v[166:169], v174 offset:1024
	ds_read_b128 v[170:173], v174 offset:2048
	ds_read_b128 v[174:177], v174 offset:3072
	ds_read_b128 v[184:187], v182 offset:32768
	ds_read_b128 v[188:191], v182 offset:33792
	ds_read_b128 v[192:195], v182 offset:34816
	ds_read_b128 v[200:203], v182 offset:35840
	ds_read_b128 v[204:207], v182 offset:36864
	ds_read_b128 v[208:211], v182 offset:37888
	ds_read_b128 v[212:215], v182 offset:38912
	ds_read_b128 v[216:219], v182 offset:39936
	s_waitcnt vmcnt(8)
	s_waitcnt lgkmcnt(0)
	s_setprio 1
	s_barrier
	v_mfma_f32_16x16x32_bf16 v[126:129], v[130:133], v[184:187], v[126:129]
	v_mfma_f32_16x16x32_bf16 v[122:125], v[138:141], v[184:187], v[122:125]
	v_mfma_f32_16x16x32_bf16 v[110:113], v[130:133], v[192:195], v[110:113]
	v_mfma_f32_16x16x32_bf16 v[106:109], v[138:141], v[192:195], v[106:109]
	v_mfma_f32_16x16x32_bf16 v[94:97], v[130:133], v[204:207], v[94:97]
	v_mfma_f32_16x16x32_bf16 v[90:93], v[138:141], v[204:207], v[90:93]
	v_mfma_f32_16x16x32_bf16 v[78:81], v[130:133], v[212:215], v[78:81]
	v_mfma_f32_16x16x32_bf16 v[74:77], v[138:141], v[212:215], v[74:77]
	v_mfma_f32_16x16x32_bf16 v[126:129], v[134:137], v[188:191], v[126:129]
	v_mfma_f32_16x16x32_bf16 v[122:125], v[142:145], v[188:191], v[122:125]
	v_mfma_f32_16x16x32_bf16 v[110:113], v[134:137], v[200:203], v[110:113]
	v_mfma_f32_16x16x32_bf16 v[106:109], v[142:145], v[200:203], v[106:109]
	v_mfma_f32_16x16x32_bf16 v[94:97], v[134:137], v[208:211], v[94:97]
	v_mfma_f32_16x16x32_bf16 v[90:93], v[142:145], v[208:211], v[90:93]
	v_mfma_f32_16x16x32_bf16 v[78:81], v[134:137], v[216:219], v[78:81]
	v_mfma_f32_16x16x32_bf16 v[74:77], v[142:145], v[216:219], v[74:77]
	v_mfma_f32_16x16x32_bf16 v[118:121], v[146:149], v[184:187], v[118:121]
	v_mfma_f32_16x16x32_bf16 v[114:117], v[170:173], v[184:187], v[114:117]
	v_mfma_f32_16x16x32_bf16 v[102:105], v[146:149], v[192:195], v[102:105]
	v_mfma_f32_16x16x32_bf16 v[98:101], v[170:173], v[192:195], v[98:101]
	v_mfma_f32_16x16x32_bf16 v[86:89], v[146:149], v[204:207], v[86:89]
	v_mfma_f32_16x16x32_bf16 v[82:85], v[170:173], v[204:207], v[82:85]
	v_mfma_f32_16x16x32_bf16 v[70:73], v[146:149], v[212:215], v[70:73]
	v_mfma_f32_16x16x32_bf16 v[66:69], v[170:173], v[212:215], v[66:69]
	v_mfma_f32_16x16x32_bf16 v[118:121], v[166:169], v[188:191], v[118:121]
	v_mfma_f32_16x16x32_bf16 v[114:117], v[174:177], v[188:191], v[114:117]
	v_mfma_f32_16x16x32_bf16 v[102:105], v[166:169], v[200:203], v[102:105]
	v_mfma_f32_16x16x32_bf16 v[98:101], v[174:177], v[200:203], v[98:101]
	v_mfma_f32_16x16x32_bf16 v[86:89], v[166:169], v[208:211], v[86:89]
	v_mfma_f32_16x16x32_bf16 v[82:85], v[174:177], v[208:211], v[82:85]
	v_mfma_f32_16x16x32_bf16 v[70:73], v[166:169], v[216:219], v[70:73]
	v_mfma_f32_16x16x32_bf16 v[66:69], v[174:177], v[216:219], v[66:69]
	s_barrier
	s_setprio 0
	s_add_i32 s36, s57, s38
	s_add_u32 s34, s34, 0x80
	s_addc_u32 s35, s35, 0
	s_mov_b32 m0, s36
	s_nop 0
	global_load_lds_dwordx4 v152, s[34:35]
	s_add_i32 m0, s36, 0x2000
	s_add_i32 s36, s58, s38
	global_load_lds_dwordx4 v156, s[34:35]
	s_add_u32 s34, s34, 0x80000
	s_addc_u32 s35, s35, 0
	s_mov_b32 m0, s36
	s_nop 0
	global_load_lds_dwordx4 v152, s[34:35]
	s_add_i32 m0, s36, 0x2000
	s_nop 0
	global_load_lds_dwordx4 v156, s[34:35]
	ds_read_b128 v[184:187], v182 offset:49152
	ds_read_b128 v[188:191], v182 offset:50176
	ds_read_b128 v[192:195], v182 offset:51200
	ds_read_b128 v[200:203], v182 offset:52224
	ds_read_b128 v[204:207], v182 offset:53248
	ds_read_b128 v[208:211], v182 offset:54272
	ds_read_b128 v[212:215], v182 offset:55296
	ds_read_b128 v[216:219], v182 offset:56320
	s_waitcnt vmcnt(6)
	s_waitcnt lgkmcnt(0)
	s_setprio 1
	s_barrier
	v_mfma_f32_16x16x32_bf16 v[62:65], v[130:133], v[184:187], v[62:65]
	v_mfma_f32_16x16x32_bf16 v[58:61], v[138:141], v[184:187], v[58:61]
	v_mfma_f32_16x16x32_bf16 v[46:49], v[130:133], v[192:195], v[46:49]
	v_mfma_f32_16x16x32_bf16 v[42:45], v[138:141], v[192:195], v[42:45]
	v_mfma_f32_16x16x32_bf16 v[30:33], v[130:133], v[204:207], v[30:33]
	v_mfma_f32_16x16x32_bf16 v[26:29], v[138:141], v[204:207], v[26:29]
	v_mfma_f32_16x16x32_bf16 v[14:17], v[130:133], v[212:215], v[14:17]
	v_mfma_f32_16x16x32_bf16 v[10:13], v[138:141], v[212:215], v[10:13]
	v_mfma_f32_16x16x32_bf16 v[62:65], v[134:137], v[188:191], v[62:65]
	v_mfma_f32_16x16x32_bf16 v[58:61], v[142:145], v[188:191], v[58:61]
	v_mfma_f32_16x16x32_bf16 v[46:49], v[134:137], v[200:203], v[46:49]
	v_mfma_f32_16x16x32_bf16 v[42:45], v[142:145], v[200:203], v[42:45]
	v_mfma_f32_16x16x32_bf16 v[30:33], v[134:137], v[208:211], v[30:33]
	v_mfma_f32_16x16x32_bf16 v[26:29], v[142:145], v[208:211], v[26:29]
	v_mfma_f32_16x16x32_bf16 v[14:17], v[134:137], v[216:219], v[14:17]
	v_mfma_f32_16x16x32_bf16 v[10:13], v[142:145], v[216:219], v[10:13]
	v_mfma_f32_16x16x32_bf16 v[54:57], v[146:149], v[184:187], v[54:57]
	v_mfma_f32_16x16x32_bf16 v[50:53], v[170:173], v[184:187], v[50:53]
	v_mfma_f32_16x16x32_bf16 v[38:41], v[146:149], v[192:195], v[38:41]
	v_mfma_f32_16x16x32_bf16 v[34:37], v[170:173], v[192:195], v[34:37]
	v_mfma_f32_16x16x32_bf16 v[22:25], v[146:149], v[204:207], v[22:25]
	v_mfma_f32_16x16x32_bf16 v[18:21], v[170:173], v[204:207], v[18:21]
	v_mfma_f32_16x16x32_bf16 v[6:9], v[146:149], v[212:215], v[6:9]
	v_mfma_f32_16x16x32_bf16 v[2:5], v[170:173], v[212:215], v[2:5]
	v_mfma_f32_16x16x32_bf16 v[54:57], v[166:169], v[188:191], v[54:57]
	v_mfma_f32_16x16x32_bf16 v[50:53], v[174:177], v[188:191], v[50:53]
	v_mfma_f32_16x16x32_bf16 v[38:41], v[166:169], v[200:203], v[38:41]
	v_mfma_f32_16x16x32_bf16 v[34:37], v[174:177], v[200:203], v[34:37]
	v_mfma_f32_16x16x32_bf16 v[22:25], v[166:169], v[208:211], v[22:25]
	v_mfma_f32_16x16x32_bf16 v[18:21], v[174:177], v[208:211], v[18:21]
	v_mfma_f32_16x16x32_bf16 v[6:9], v[166:169], v[216:219], v[6:9]
	v_mfma_f32_16x16x32_bf16 v[2:5], v[174:177], v[216:219], v[2:5]
	s_barrier
	s_setprio 0
	s_add_i32 s56, s56, 2
	s_add_u32 s30, s30, 0x100
	s_addc_u32 s31, s31, 0
	s_add_u32 s52, s52, 0x100
	s_addc_u32 s53, s53, 0
	s_cmp_gt_u32 s56, 29
	s_cbranch_scc0 .LBB0_857
	s_and_b64 vcc, exec, s[10:11]
	s_cbranch_vccz .LBB0_860
	s_barrier

; #define PG8_STAGE(bufoff, gbase, voff) do { _Pragma("unroll") for (int _i = 0; _i < 2; ++_i) \
;         __builtin_amdgcn_global_load_lds((const unsigned*)((const char*)(gbase) + (voff)[_i]), (PG8_LAS unsigned*)(lds + (bufoff) + ldsw + _i * 8192), 16, 0, 0); } while (0)
; #define PG8_LDA(dst, b, h) do { _Pragma("unroll") for (int m = 0; m < 4; ++m) _Pragma("unroll") for (int k = 0; k < 2; ++k) dst[m][k] = *(const PG8_LAS bf16x8*)(lds + PG8_SA(b, h) + aoff + m * 2048 + k * 1024); } while (0)
; #define PG8_LDB(dst, b, h) do { _Pragma("unroll") for (int n = 0; n < 2; ++n) _Pragma("unroll") for (int k = 0; k < 2; ++k) dst[n][k] = *(const PG8_LAS bf16x8*)(lds + PG8_SB(b, h) + boff + n * 2048 + k * 1024); } while (0)
; #define PG8_MMA(ai, bj, At, Bt) do { __builtin_amdgcn_s_setprio(1); _Pragma("unroll") for (int m = 0; m < 4; ++m) _Pragma("unroll") for (int n = 0; n < 2; ++n) _Pragma("unroll") for (int k = 0; k < 2; ++k) \
;         acc[ai][bj][m][n] = __builtin_amdgcn_mfma_f32_16x16x32_bf16(Bt[n][k], At[m][k], acc[ai][bj][m][n], 0, 0, 0); __builtin_amdgcn_s_setprio(0); } while (0)
; #define PG8_WAIT_V(n) asm volatile("s_waitcnt vmcnt(" #n ")" ::: "memory")
; #define PG8_WAIT_L(n) asm volatile("s_waitcnt lgkmcnt(" #n ")" ::: "memory")
; #define PG8_BAR __builtin_amdgcn_s_barrier()
; #define PG8_SCHED __builtin_amdgcn_sched_barrier(0)
; template <class Epi, class Sched, bool ALIGN_EPI = false, bool SP2 = false>
; __device__ __forceinline__ void gemm_phase(PG8_LAS unsigned char* lds, const Gemm g, const Sched& S, const Epi& E) {
;     ...
;             PG8_LDB(B0, 0, 0); PG8_LDB(B1, 0, 1); PG8_SCHED; PG8_LDA(At, 0, 0); PG8_STAGE(PG8_SA(1, 1), a1 + hstep, voffA);
;             PG8_WAIT_V(8); PG8_WAIT_L(0); PG8_BAR; PG8_MMA(0, 0, At, B0); PG8_MMA(0, 1, At, B1); PG8_BAR; PG8_SCHED;
;             PG8_LDA(At, 0, 1); PG8_STAGE(PG8_SB(0, 0), b2, voffB); PG8_STAGE(PG8_SB(0, 1), b2 + hstep, voffB); PG8_STAGE(PG8_SA(0, 0), a2, voffA);
;             PG8_WAIT_V(8); PG8_WAIT_L(0); PG8_BAR; PG8_MMA(1, 0, At, B0); PG8_MMA(1, 1, At, B1); PG8_BAR; PG8_SCHED;
.LBB0_884:
	s_add_u32 s34, s30, 0xfff80000
	s_addc_u32 s35, s31, -1
	s_mov_b32 m0, s43
	s_nop 0
	global_load_lds_dwordx4 v178, s[34:35]
	s_mov_b32 m0, s44
	s_nop 0
	global_load_lds_dwordx4 v182, s[34:35]
	s_add_u32 s34, s34, 0x80
	s_addc_u32 s35, s35, 0
	s_cmp_eq_u32 s56, 28
	s_cselect_b32 s37, s15, s35
	s_cselect_b32 s36, s50, s34
	s_cselect_b32 s35, s13, s53
	s_cselect_b32 s34, s51, s52
	s_add_i32 m0, s29, 0xc000
	s_nop 0
	global_load_lds_dwordx4 v186, s[30:31]
	s_add_i32 m0, s29, 0xe000
	s_nop 0
	global_load_lds_dwordx4 v188, s[30:31]
	ds_read_b128 v[130:133], v211
	ds_read_b128 v[134:137], v211 offset:1024
	ds_read_b128 v[138:141], v211 offset:2048
	ds_read_b128 v[142:145], v211 offset:3072
	ds_read_b128 v[146:149], v212
	ds_read_b128 v[150:153], v212 offset:1024
	ds_read_b128 v[154:157], v212 offset:2048
	ds_read_b128 v[158:161], v212 offset:3072
	ds_read_b128 v[162:165], v213
	ds_read_b128 v[166:169], v213 offset:1024
	ds_read_b128 v[170:173], v213 offset:2048
	ds_read_b128 v[174:177], v213 offset:3072
	ds_read_b128 v[194:197], v213 offset:4096
	ds_read_b128 v[200:203], v213 offset:5120
	ds_read_b128 v[204:207], v213 offset:6144
	ds_read_b128 v[214:217], v213 offset:7168
	s_waitcnt vmcnt(8)
	s_waitcnt lgkmcnt(0)
	s_setprio 1
	s_barrier
	v_mfma_f32_16x16x32_bf16 v[126:129], v[130:133], v[162:165], v[126:129]
	v_mfma_f32_16x16x32_bf16 v[122:125], v[138:141], v[162:165], v[122:125]
	v_mfma_f32_16x16x32_bf16 v[110:113], v[130:133], v[170:173], v[110:113]
	v_mfma_f32_16x16x32_bf16 v[106:109], v[138:141], v[170:173], v[106:109]
	v_mfma_f32_16x16x32_bf16 v[94:97], v[130:133], v[194:197], v[94:97]
	v_mfma_f32_16x16x32_bf16 v[90:93], v[138:141], v[194:197], v[90:93]
	v_mfma_f32_16x16x32_bf16 v[78:81], v[130:133], v[204:207], v[78:81]
	v_mfma_f32_16x16x32_bf16 v[74:77], v[138:141], v[204:207], v[74:77]
	v_mfma_f32_16x16x32_bf16 v[126:129], v[134:137], v[166:169], v[126:129]
	v_mfma_f32_16x16x32_bf16 v[122:125], v[142:145], v[166:169], v[122:125]
	v_mfma_f32_16x16x32_bf16 v[110:113], v[134:137], v[174:177], v[110:113]
	v_mfma_f32_16x16x32_bf16 v[106:109], v[142:145], v[174:177], v[106:109]
	v_mfma_f32_16x16x32_bf16 v[94:97], v[134:137], v[200:203], v[94:97]
	v_mfma_f32_16x16x32_bf16 v[90:93], v[142:145], v[200:203], v[90:93]
	v_mfma_f32_16x16x32_bf16 v[78:81], v[134:137], v[214:217], v[78:81]
	v_mfma_f32_16x16x32_bf16 v[74:77], v[142:145], v[214:217], v[74:77]
	v_mfma_f32_16x16x32_bf16 v[118:121], v[146:149], v[162:165], v[118:121]
	v_mfma_f32_16x16x32_bf16 v[114:117], v[154:157], v[162:165], v[114:117]
	v_mfma_f32_16x16x32_bf16 v[102:105], v[146:149], v[170:173], v[102:105]
	v_mfma_f32_16x16x32_bf16 v[98:101], v[154:157], v[170:173], v[98:101]
	v_mfma_f32_16x16x32_bf16 v[86:89], v[146:149], v[194:197], v[86:89]
	v_mfma_f32_16x16x32_bf16 v[82:85], v[154:157], v[194:197], v[82:85]
	v_mfma_f32_16x16x32_bf16 v[70:73], v[146:149], v[204:207], v[70:73]
	v_mfma_f32_16x16x32_bf16 v[66:69], v[154:157], v[204:207], v[66:69]
	v_mfma_f32_16x16x32_bf16 v[118:121], v[150:153], v[166:169], v[118:121]
	v_mfma_f32_16x16x32_bf16 v[114:117], v[158:161], v[166:169], v[114:117]
	v_mfma_f32_16x16x32_bf16 v[102:105], v[150:153], v[174:177], v[102:105]
	v_mfma_f32_16x16x32_bf16 v[98:101], v[158:161], v[174:177], v[98:101]
	v_mfma_f32_16x16x32_bf16 v[86:89], v[150:153], v[200:203], v[86:89]
	v_mfma_f32_16x16x32_bf16 v[82:85], v[158:161], v[200:203], v[82:85]
	v_mfma_f32_16x16x32_bf16 v[70:73], v[150:153], v[214:217], v[70:73]
	v_mfma_f32_16x16x32_bf16 v[66:69], v[158:161], v[214:217], v[66:69]
	s_barrier
	s_setprio 0
	s_add_i32 s57, s46, s38
	s_mov_b32 m0, s57
	s_nop 0
	global_load_lds_dwordx4 v180, s[34:35]
	s_add_i32 m0, s57, 0x2000
	s_add_u32 s58, s34, 0x80000
	s_addc_u32 s59, s35, 0
	s_add_i32 s57, s47, s38
	global_load_lds_dwordx4 v184, s[34:35]
	s_mov_b32 m0, s57
	s_nop 0
	global_load_lds_dwordx4 v180, s[58:59]
	s_add_i32 m0, s57, 0x2000
	s_nop 0
	global_load_lds_dwordx4 v184, s[58:59]
	ds_read_b128 v[162:165], v213 offset:16384
	ds_read_b128 v[166:169], v213 offset:17408
	ds_read_b128 v[170:173], v213 offset:18432
	ds_read_b128 v[174:177], v213 offset:19456
	ds_read_b128 v[194:197], v213 offset:20480
	ds_read_b128 v[200:203], v213 offset:21504
	ds_read_b128 v[204:207], v213 offset:22528
	ds_read_b128 v[214:217], v213 offset:23552
	s_waitcnt vmcnt(6)
	s_waitcnt lgkmcnt(0)
	s_setprio 1
	s_barrier
	v_mfma_f32_16x16x32_bf16 v[62:65], v[130:133], v[162:165], v[62:65]
	v_mfma_f32_16x16x32_bf16 v[58:61], v[138:141], v[162:165], v[58:61]
	v_mfma_f32_16x16x32_bf16 v[46:49], v[130:133], v[170:173], v[46:49]
	v_mfma_f32_16x16x32_bf16 v[42:45], v[138:141], v[170:173], v[42:45]
	v_mfma_f32_16x16x32_bf16 v[30:33], v[130:133], v[194:197], v[30:33]
	v_mfma_f32_16x16x32_bf16 v[26:29], v[138:141], v[194:197], v[26:29]
	v_mfma_f32_16x16x32_bf16 v[14:17], v[130:133], v[204:207], v[14:17]
	v_mfma_f32_16x16x32_bf16 v[10:13], v[138:141], v[204:207], v[10:13]
	v_mfma_f32_16x16x32_bf16 v[62:65], v[134:137], v[166:169], v[62:65]
	v_mfma_f32_16x16x32_bf16 v[58:61], v[142:145], v[166:169], v[58:61]
	v_mfma_f32_16x16x32_bf16 v[46:49], v[134:137], v[174:177], v[46:49]
	v_mfma_f32_16x16x32_bf16 v[42:45], v[142:145], v[174:177], v[42:45]
	v_mfma_f32_16x16x32_bf16 v[30:33], v[134:137], v[200:203], v[30:33]
	v_mfma_f32_16x16x32_bf16 v[26:29], v[142:145], v[200:203], v[26:29]
	v_mfma_f32_16x16x32_bf16 v[14:17], v[134:137], v[214:217], v[14:17]
	v_mfma_f32_16x16x32_bf16 v[10:13], v[142:145], v[214:217], v[10:13]
	v_mfma_f32_16x16x32_bf16 v[54:57], v[146:149], v[162:165], v[54:57]
	v_mfma_f32_16x16x32_bf16 v[50:53], v[154:157], v[162:165], v[50:53]
	v_mfma_f32_16x16x32_bf16 v[38:41], v[146:149], v[170:173], v[38:41]
	v_mfma_f32_16x16x32_bf16 v[34:37], v[154:157], v[170:173], v[34:37]
	v_mfma_f32_16x16x32_bf16 v[22:25], v[146:149], v[194:197], v[22:25]
	v_mfma_f32_16x16x32_bf16 v[18:21], v[154:157], v[194:197], v[18:21]
	v_mfma_f32_16x16x32_bf16 v[6:9], v[146:149], v[204:207], v[6:9]
	v_mfma_f32_16x16x32_bf16 v[2:5], v[154:157], v[204:207], v[2:5]
	v_mfma_f32_16x16x32_bf16 v[54:57], v[150:153], v[166:169], v[54:57]
	v_mfma_f32_16x16x32_bf16 v[50:53], v[158:161], v[166:169], v[50:53]
	v_mfma_f32_16x16x32_bf16 v[38:41], v[150:153], v[174:177], v[38:41]
	v_mfma_f32_16x16x32_bf16 v[34:37], v[158:161], v[174:177], v[34:37]
	v_mfma_f32_16x16x32_bf16 v[22:25], v[150:153], v[200:203], v[22:25]
	v_mfma_f32_16x16x32_bf16 v[18:21], v[158:161], v[200:203], v[18:21]
	v_mfma_f32_16x16x32_bf16 v[6:9], v[150:153], v[214:217], v[6:9]
	v_mfma_f32_16x16x32_bf16 v[2:5], v[158:161], v[214:217], v[2:5]
	s_barrier
; #define PG8_STAGE(bufoff, gbase, voff) do { _Pragma("unroll") for (int _i = 0; _i < 2; ++_i) \
;         __builtin_amdgcn_global_load_lds((const unsigned*)((const char*)(gbase) + (voff)[_i]), (PG8_LAS unsigned*)(lds + (bufoff) + ldsw + _i * 8192), 16, 0, 0); } while (0)
; #define PG8_LDA(dst, b, h) do { _Pragma("unroll") for (int m = 0; m < 4; ++m) _Pragma("unroll") for (int k = 0; k < 2; ++k) dst[m][k] = *(const PG8_LAS bf16x8*)(lds + PG8_SA(b, h) + aoff + m * 2048 + k * 1024); } while (0)
; #define PG8_LDB(dst, b, h) do { _Pragma("unroll") for (int n = 0; n < 2; ++n) _Pragma("unroll") for (int k = 0; k < 2; ++k) dst[n][k] = *(const PG8_LAS bf16x8*)(lds + PG8_SB(b, h) + boff + n * 2048 + k * 1024); } while (0)
; #define PG8_MMA(ai, bj, At, Bt) do { __builtin_amdgcn_s_setprio(1); _Pragma("unroll") for (int m = 0; m < 4; ++m) _Pragma("unroll") for (int n = 0; n < 2; ++n) _Pragma("unroll") for (int k = 0; k < 2; ++k) \
;         acc[ai][bj][m][n] = __builtin_amdgcn_mfma_f32_16x16x32_bf16(Bt[n][k], At[m][k], acc[ai][bj][m][n], 0, 0, 0); __builtin_amdgcn_s_setprio(0); } while (0)
; #define PG8_WAIT_V(n) asm volatile("s_waitcnt vmcnt(" #n ")" ::: "memory")
; #define PG8_WAIT_L(n) asm volatile("s_waitcnt lgkmcnt(" #n ")" ::: "memory")
; #define PG8_BAR __builtin_amdgcn_s_barrier()
; #define PG8_SCHED __builtin_amdgcn_sched_barrier(0)
; template <class Epi, class Sched, bool ALIGN_EPI = false, bool SP2 = false>
; __device__ __forceinline__ void gemm_phase(PG8_LAS unsigned char* lds, const Gemm g, const Sched& S, const Epi& E) {
;     ...
;             PG8_LDB(B0, 1, 0); PG8_LDB(B1, 1, 1); PG8_SCHED; PG8_LDA(At, 1, 0); PG8_STAGE(PG8_SA(0, 1), a2 + hstep, voffA);
;             PG8_WAIT_V(8); PG8_WAIT_L(0); PG8_BAR; PG8_MMA(0, 0, At, B0); PG8_MMA(0, 1, At, B1); PG8_BAR; PG8_SCHED;
;             PG8_LDA(At, 1, 1); PG8_STAGE(PG8_SB(1, 0), b3, voffB); PG8_STAGE(PG8_SB(1, 1), b3 + hstep, voffB); PG8_STAGE(PG8_SA(1, 0), a3, voffA);
;             PG8_WAIT_V(8); PG8_WAIT_L(0); PG8_BAR; PG8_MMA(1, 0, At, B0); PG8_MMA(1, 1, At, B1); PG8_BAR; PG8_SCHED;
;     ...
;         if constexpr (ALIGN_EPI) { if (wr == 0) PG8_BAR; }
	s_setprio 0
	s_mov_b32 m0, s29
	s_nop 0
	global_load_lds_dwordx4 v178, s[36:37]
	s_mov_b32 m0, s39
	s_nop 0
	global_load_lds_dwordx4 v182, s[36:37]
	s_add_i32 s57, 0, 0x18000
	s_add_i32 s58, 0, 0x1c000
	s_add_u32 s36, s36, 0x80000
	s_addc_u32 s37, s37, 0
	s_mov_b32 m0, s40
	s_nop 0
	global_load_lds_dwordx4 v178, s[36:37]
	s_mov_b32 m0, s41
	s_nop 0
	global_load_lds_dwordx4 v182, s[36:37]
	v_add_u32_e32 v142, s57, v199
	v_add_u32_e32 v158, s58, v199
	ds_read_b128 v[130:133], v142
	ds_read_b128 v[134:137], v142 offset:1024
	ds_read_b128 v[138:141], v142 offset:2048
	ds_read_b128 v[142:145], v142 offset:3072
	ds_read_b128 v[146:149], v158
	ds_read_b128 v[150:153], v158 offset:1024
	ds_read_b128 v[154:157], v158 offset:2048
	ds_read_b128 v[158:161], v158 offset:3072
	ds_read_b128 v[162:165], v213 offset:32768
	ds_read_b128 v[166:169], v213 offset:33792
	ds_read_b128 v[170:173], v213 offset:34816
	ds_read_b128 v[174:177], v213 offset:35840
	ds_read_b128 v[194:197], v213 offset:36864
	ds_read_b128 v[200:203], v213 offset:37888
	ds_read_b128 v[204:207], v213 offset:38912
	ds_read_b128 v[214:217], v213 offset:39936
	s_waitcnt vmcnt(8)
	s_waitcnt lgkmcnt(0)
	s_setprio 1
	s_barrier
	v_mfma_f32_16x16x32_bf16 v[126:129], v[130:133], v[162:165], v[126:129]
	v_mfma_f32_16x16x32_bf16 v[122:125], v[138:141], v[162:165], v[122:125]
	v_mfma_f32_16x16x32_bf16 v[110:113], v[130:133], v[170:173], v[110:113]
	v_mfma_f32_16x16x32_bf16 v[106:109], v[138:141], v[170:173], v[106:109]
	v_mfma_f32_16x16x32_bf16 v[94:97], v[130:133], v[194:197], v[94:97]
	v_mfma_f32_16x16x32_bf16 v[90:93], v[138:141], v[194:197], v[90:93]
	v_mfma_f32_16x16x32_bf16 v[78:81], v[130:133], v[204:207], v[78:81]
	v_mfma_f32_16x16x32_bf16 v[74:77], v[138:141], v[204:207], v[74:77]
	v_mfma_f32_16x16x32_bf16 v[126:129], v[134:137], v[166:169], v[126:129]
	v_mfma_f32_16x16x32_bf16 v[122:125], v[142:145], v[166:169], v[122:125]
	v_mfma_f32_16x16x32_bf16 v[110:113], v[134:137], v[174:177], v[110:113]
	v_mfma_f32_16x16x32_bf16 v[106:109], v[142:145], v[174:177], v[106:109]
	v_mfma_f32_16x16x32_bf16 v[94:97], v[134:137], v[200:203], v[94:97]
	v_mfma_f32_16x16x32_bf16 v[90:93], v[142:145], v[200:203], v[90:93]
	v_mfma_f32_16x16x32_bf16 v[78:81], v[134:137], v[214:217], v[78:81]
	v_mfma_f32_16x16x32_bf16 v[74:77], v[142:145], v[214:217], v[74:77]
	v_mfma_f32_16x16x32_bf16 v[118:121], v[146:149], v[162:165], v[118:121]
	v_mfma_f32_16x16x32_bf16 v[114:117], v[154:157], v[162:165], v[114:117]
	v_mfma_f32_16x16x32_bf16 v[102:105], v[146:149], v[170:173], v[102:105]
	v_mfma_f32_16x16x32_bf16 v[98:101], v[154:157], v[170:173], v[98:101]
	v_mfma_f32_16x16x32_bf16 v[86:89], v[146:149], v[194:197], v[86:89]
	v_mfma_f32_16x16x32_bf16 v[82:85], v[154:157], v[194:197], v[82:85]
	v_mfma_f32_16x16x32_bf16 v[70:73], v[146:149], v[204:207], v[70:73]
	v_mfma_f32_16x16x32_bf16 v[66:69], v[154:157], v[204:207], v[66:69]
	v_mfma_f32_16x16x32_bf16 v[118:121], v[150:153], v[166:169], v[118:121]
	v_mfma_f32_16x16x32_bf16 v[114:117], v[158:161], v[166:169], v[114:117]
	v_mfma_f32_16x16x32_bf16 v[102:105], v[150:153], v[174:177], v[102:105]
	v_mfma_f32_16x16x32_bf16 v[98:101], v[158:161], v[174:177], v[98:101]
	v_mfma_f32_16x16x32_bf16 v[86:89], v[150:153], v[200:203], v[86:89]
	v_mfma_f32_16x16x32_bf16 v[82:85], v[158:161], v[200:203], v[82:85]
	v_mfma_f32_16x16x32_bf16 v[70:73], v[150:153], v[214:217], v[70:73]
	v_mfma_f32_16x16x32_bf16 v[66:69], v[158:161], v[214:217], v[66:69]
	s_barrier
	s_setprio 0
	s_add_i32 s36, s57, s38
	s_add_u32 s34, s34, 0x80
	s_addc_u32 s35, s35, 0
	s_mov_b32 m0, s36
	s_nop 0
	global_load_lds_dwordx4 v180, s[34:35]
	s_add_i32 m0, s36, 0x2000
	s_add_i32 s36, s58, s38
	global_load_lds_dwordx4 v184, s[34:35]
	s_add_u32 s34, s34, 0x80000
	s_addc_u32 s35, s35, 0
	s_mov_b32 m0, s36
	s_nop 0
	global_load_lds_dwordx4 v180, s[34:35]
	s_add_i32 m0, s36, 0x2000
	s_nop 0
	global_load_lds_dwordx4 v184, s[34:35]
	ds_read_b128 v[162:165], v213 offset:49152
	ds_read_b128 v[166:169], v213 offset:50176
	ds_read_b128 v[170:173], v213 offset:51200
	ds_read_b128 v[174:177], v213 offset:52224
	ds_read_b128 v[194:197], v213 offset:53248
	ds_read_b128 v[200:203], v213 offset:54272
	ds_read_b128 v[204:207], v213 offset:55296
	ds_read_b128 v[214:217], v213 offset:56320
	s_waitcnt vmcnt(6)
	s_waitcnt lgkmcnt(0)
	s_setprio 1
	s_barrier
	v_mfma_f32_16x16x32_bf16 v[62:65], v[130:133], v[162:165], v[62:65]
	v_mfma_f32_16x16x32_bf16 v[58:61], v[138:141], v[162:165], v[58:61]
	v_mfma_f32_16x16x32_bf16 v[46:49], v[130:133], v[170:173], v[46:49]
	v_mfma_f32_16x16x32_bf16 v[42:45], v[138:141], v[170:173], v[42:45]
	v_mfma_f32_16x16x32_bf16 v[30:33], v[130:133], v[194:197], v[30:33]
	v_mfma_f32_16x16x32_bf16 v[26:29], v[138:141], v[194:197], v[26:29]
	v_mfma_f32_16x16x32_bf16 v[14:17], v[130:133], v[204:207], v[14:17]
	v_mfma_f32_16x16x32_bf16 v[10:13], v[138:141], v[204:207], v[10:13]
	v_mfma_f32_16x16x32_bf16 v[62:65], v[134:137], v[166:169], v[62:65]
	v_mfma_f32_16x16x32_bf16 v[58:61], v[142:145], v[166:169], v[58:61]
	v_mfma_f32_16x16x32_bf16 v[46:49], v[134:137], v[174:177], v[46:49]
	v_mfma_f32_16x16x32_bf16 v[42:45], v[142:145], v[174:177], v[42:45]
	v_mfma_f32_16x16x32_bf16 v[30:33], v[134:137], v[200:203], v[30:33]
	v_mfma_f32_16x16x32_bf16 v[26:29], v[142:145], v[200:203], v[26:29]
	v_mfma_f32_16x16x32_bf16 v[14:17], v[134:137], v[214:217], v[14:17]
	v_mfma_f32_16x16x32_bf16 v[10:13], v[142:145], v[214:217], v[10:13]
	v_mfma_f32_16x16x32_bf16 v[54:57], v[146:149], v[162:165], v[54:57]
	v_mfma_f32_16x16x32_bf16 v[50:53], v[154:157], v[162:165], v[50:53]
	v_mfma_f32_16x16x32_bf16 v[38:41], v[146:149], v[170:173], v[38:41]
	v_mfma_f32_16x16x32_bf16 v[34:37], v[154:157], v[170:173], v[34:37]
	v_mfma_f32_16x16x32_bf16 v[22:25], v[146:149], v[194:197], v[22:25]
	v_mfma_f32_16x16x32_bf16 v[18:21], v[154:157], v[194:197], v[18:21]
	v_mfma_f32_16x16x32_bf16 v[6:9], v[146:149], v[204:207], v[6:9]
	v_mfma_f32_16x16x32_bf16 v[2:5], v[154:157], v[204:207], v[2:5]
	v_mfma_f32_16x16x32_bf16 v[54:57], v[150:153], v[166:169], v[54:57]
	v_mfma_f32_16x16x32_bf16 v[50:53], v[158:161], v[166:169], v[50:53]
	v_mfma_f32_16x16x32_bf16 v[38:41], v[150:153], v[174:177], v[38:41]
	v_mfma_f32_16x16x32_bf16 v[34:37], v[158:161], v[174:177], v[34:37]
	v_mfma_f32_16x16x32_bf16 v[22:25], v[150:153], v[200:203], v[22:25]
	v_mfma_f32_16x16x32_bf16 v[18:21], v[158:161], v[200:203], v[18:21]
	v_mfma_f32_16x16x32_bf16 v[6:9], v[150:153], v[214:217], v[6:9]
	v_mfma_f32_16x16x32_bf16 v[2:5], v[158:161], v[214:217], v[2:5]
	s_barrier
	s_setprio 0
	s_add_i32 s56, s56, 2
	s_add_u32 s30, s30, 0x100
	s_addc_u32 s31, s31, 0
	s_add_u32 s52, s52, 0x100
	s_addc_u32 s53, s53, 0
	s_cmp_gt_u32 s56, 29
	s_cbranch_scc0 .LBB0_884
	s_and_b64 vcc, exec, s[10:11]
	s_cbranch_vccz .LBB0_887
	s_barrier

; #define PG8_STAGE(bufoff, gbase, voff) do { _Pragma("unroll") for (int _i = 0; _i < 2; ++_i) \
;         __builtin_amdgcn_global_load_lds((const unsigned*)((const char*)(gbase) + (voff)[_i]), (PG8_LAS unsigned*)(lds + (bufoff) + ldsw + _i * 8192), 16, 0, 0); } while (0)
; #define PG8_LDA(dst, b, h) do { _Pragma("unroll") for (int m = 0; m < 4; ++m) _Pragma("unroll") for (int k = 0; k < 2; ++k) dst[m][k] = *(const PG8_LAS bf16x8*)(lds + PG8_SA(b, h) + aoff + m * 2048 + k * 1024); } while (0)
; #define PG8_LDB(dst, b, h) do { _Pragma("unroll") for (int n = 0; n < 2; ++n) _Pragma("unroll") for (int k = 0; k < 2; ++k) dst[n][k] = *(const PG8_LAS bf16x8*)(lds + PG8_SB(b, h) + boff + n * 2048 + k * 1024); } while (0)
; #define PG8_MMA(ai, bj, At, Bt) do { __builtin_amdgcn_s_setprio(1); _Pragma("unroll") for (int m = 0; m < 4; ++m) _Pragma("unroll") for (int n = 0; n < 2; ++n) _Pragma("unroll") for (int k = 0; k < 2; ++k) \
;         acc[ai][bj][m][n] = __builtin_amdgcn_mfma_f32_16x16x32_bf16(Bt[n][k], At[m][k], acc[ai][bj][m][n], 0, 0, 0); __builtin_amdgcn_s_setprio(0); } while (0)
; #define PG8_WAIT_V(n) asm volatile("s_waitcnt vmcnt(" #n ")" ::: "memory")
; #define PG8_WAIT_L(n) asm volatile("s_waitcnt lgkmcnt(" #n ")" ::: "memory")
; #define PG8_BAR __builtin_amdgcn_s_barrier()
; #define PG8_SCHED __builtin_amdgcn_sched_barrier(0)
; template <class Epi, class Sched, bool ALIGN_EPI = false, bool SP2 = false>
; __device__ __forceinline__ void gemm_phase(PG8_LAS unsigned char* lds, const Gemm g, const Sched& S, const Epi& E) {
;     ...
;             PG8_LDB(B0, 0, 0); PG8_LDB(B1, 0, 1); PG8_SCHED; PG8_LDA(At, 0, 0); PG8_STAGE(PG8_SA(1, 1), a1 + hstep, voffA);
;             PG8_WAIT_V(8); PG8_WAIT_L(0); PG8_BAR; PG8_MMA(0, 0, At, B0); PG8_MMA(0, 1, At, B1); PG8_BAR; PG8_SCHED;
;             PG8_LDA(At, 0, 1); PG8_STAGE(PG8_SB(0, 0), b2, voffB); PG8_STAGE(PG8_SB(0, 1), b2 + hstep, voffB); PG8_STAGE(PG8_SA(0, 0), a2, voffA);
;             PG8_WAIT_V(8); PG8_WAIT_L(0); PG8_BAR; PG8_MMA(1, 0, At, B0); PG8_MMA(1, 1, At, B1); PG8_BAR; PG8_SCHED;
.LBB0_959:
	s_add_u32 s30, s28, 0xfff00000
	s_addc_u32 s31, s29, -1
	s_mov_b32 m0, s41
	s_nop 0
	global_load_lds_dwordx4 v138, s[30:31]
	s_mov_b32 m0, s42
	s_nop 0
	global_load_lds_dwordx4 v142, s[30:31]
	s_add_u32 s30, s30, 0x80
	s_addc_u32 s31, s31, 0
	s_cmp_eq_u32 s51, 60
	s_cselect_b32 s35, s13, s31
	s_cselect_b32 s34, s47, s30
	s_cselect_b32 s31, s11, s50
	s_cselect_b32 s30, s48, s49
	s_add_i32 m0, s27, 0xc000
	s_nop 0
	global_load_lds_dwordx4 v146, s[28:29]
	s_add_i32 m0, s27, 0xe000
	s_nop 0
	global_load_lds_dwordx4 v148, s[28:29]
	ds_read_b128 v[130:133], v164
	ds_read_b128 v[134:137], v164 offset:1024
	ds_read_b128 v[154:157], v164 offset:2048
	ds_read_b128 v[158:161], v164 offset:3072
	ds_read_b128 v[168:171], v165
	ds_read_b128 v[172:175], v165 offset:1024
	ds_read_b128 v[176:179], v165 offset:2048
	ds_read_b128 v[180:183], v165 offset:3072
	ds_read_b128 v[184:187], v166
	ds_read_b128 v[188:191], v166 offset:1024
	ds_read_b128 v[192:195], v166 offset:2048
	ds_read_b128 v[200:203], v166 offset:3072
	ds_read_b128 v[204:207], v166 offset:4096
	ds_read_b128 v[208:211], v166 offset:5120
	ds_read_b128 v[212:215], v166 offset:6144
	ds_read_b128 v[216:219], v166 offset:7168
	s_waitcnt vmcnt(8)
	s_waitcnt lgkmcnt(0)
	s_setprio 1
	s_barrier
	v_mfma_f32_16x16x32_bf16 v[126:129], v[130:133], v[184:187], v[126:129]
	v_mfma_f32_16x16x32_bf16 v[122:125], v[154:157], v[184:187], v[122:125]
	v_mfma_f32_16x16x32_bf16 v[118:121], v[130:133], v[192:195], v[118:121]
	v_mfma_f32_16x16x32_bf16 v[114:117], v[154:157], v[192:195], v[114:117]
	v_mfma_f32_16x16x32_bf16 v[110:113], v[130:133], v[204:207], v[110:113]
	v_mfma_f32_16x16x32_bf16 v[102:105], v[154:157], v[204:207], v[102:105]
	v_mfma_f32_16x16x32_bf16 v[82:85], v[130:133], v[212:215], v[82:85]
	v_mfma_f32_16x16x32_bf16 v[74:77], v[154:157], v[212:215], v[74:77]
	v_mfma_f32_16x16x32_bf16 v[126:129], v[134:137], v[188:191], v[126:129]
	v_mfma_f32_16x16x32_bf16 v[122:125], v[158:161], v[188:191], v[122:125]
	v_mfma_f32_16x16x32_bf16 v[118:121], v[134:137], v[200:203], v[118:121]
	v_mfma_f32_16x16x32_bf16 v[114:117], v[158:161], v[200:203], v[114:117]
	v_mfma_f32_16x16x32_bf16 v[110:113], v[134:137], v[208:211], v[110:113]
	v_mfma_f32_16x16x32_bf16 v[102:105], v[158:161], v[208:211], v[102:105]
	v_mfma_f32_16x16x32_bf16 v[82:85], v[134:137], v[216:219], v[82:85]
	v_mfma_f32_16x16x32_bf16 v[74:77], v[158:161], v[216:219], v[74:77]
	v_mfma_f32_16x16x32_bf16 v[106:109], v[168:171], v[184:187], v[106:109]
	v_mfma_f32_16x16x32_bf16 v[98:101], v[176:179], v[184:187], v[98:101]
	v_mfma_f32_16x16x32_bf16 v[94:97], v[168:171], v[192:195], v[94:97]
	v_mfma_f32_16x16x32_bf16 v[90:93], v[176:179], v[192:195], v[90:93]
	v_mfma_f32_16x16x32_bf16 v[86:89], v[168:171], v[204:207], v[86:89]
	v_mfma_f32_16x16x32_bf16 v[78:81], v[176:179], v[204:207], v[78:81]
	v_mfma_f32_16x16x32_bf16 v[70:73], v[168:171], v[212:215], v[70:73]
	v_mfma_f32_16x16x32_bf16 v[66:69], v[176:179], v[212:215], v[66:69]
	v_mfma_f32_16x16x32_bf16 v[106:109], v[172:175], v[188:191], v[106:109]
	v_mfma_f32_16x16x32_bf16 v[98:101], v[180:183], v[188:191], v[98:101]
	v_mfma_f32_16x16x32_bf16 v[94:97], v[172:175], v[200:203], v[94:97]
	v_mfma_f32_16x16x32_bf16 v[90:93], v[180:183], v[200:203], v[90:93]
	v_mfma_f32_16x16x32_bf16 v[86:89], v[172:175], v[208:211], v[86:89]
	v_mfma_f32_16x16x32_bf16 v[78:81], v[180:183], v[208:211], v[78:81]
	v_mfma_f32_16x16x32_bf16 v[70:73], v[172:175], v[216:219], v[70:73]
	v_mfma_f32_16x16x32_bf16 v[66:69], v[180:183], v[216:219], v[66:69]
	s_barrier
	s_setprio 0
	s_add_i32 s52, s44, s36
	s_mov_b32 m0, s52
	s_nop 0
	global_load_lds_dwordx4 v140, s[30:31]
	s_add_i32 m0, s52, 0x2000
	s_add_u32 s52, s30, 0x100000
	s_addc_u32 s53, s31, 0
	s_add_i32 s54, s45, s36
	global_load_lds_dwordx4 v144, s[30:31]
	s_mov_b32 m0, s54
	s_nop 0
	global_load_lds_dwordx4 v140, s[52:53]
	s_add_i32 m0, s54, 0x2000
	s_nop 0
	global_load_lds_dwordx4 v144, s[52:53]
	ds_read_b128 v[184:187], v166 offset:16384
	ds_read_b128 v[188:191], v166 offset:17408
	ds_read_b128 v[192:195], v166 offset:18432
	ds_read_b128 v[200:203], v166 offset:19456
	ds_read_b128 v[204:207], v166 offset:20480
	ds_read_b128 v[208:211], v166 offset:21504
	ds_read_b128 v[212:215], v166 offset:22528
	ds_read_b128 v[216:219], v166 offset:23552
	s_waitcnt vmcnt(6)
	s_waitcnt lgkmcnt(0)
	s_setprio 1
	s_barrier
	v_mfma_f32_16x16x32_bf16 v[62:65], v[130:133], v[184:187], v[62:65]
	v_mfma_f32_16x16x32_bf16 v[58:61], v[154:157], v[184:187], v[58:61]
	v_mfma_f32_16x16x32_bf16 v[50:53], v[130:133], v[192:195], v[50:53]
	v_mfma_f32_16x16x32_bf16 v[42:45], v[154:157], v[192:195], v[42:45]
	v_mfma_f32_16x16x32_bf16 v[34:37], v[130:133], v[204:207], v[34:37]
	v_mfma_f32_16x16x32_bf16 v[26:29], v[154:157], v[204:207], v[26:29]
	v_mfma_f32_16x16x32_bf16 v[18:21], v[130:133], v[212:215], v[18:21]
	v_mfma_f32_16x16x32_bf16 v[10:13], v[154:157], v[212:215], v[10:13]
	v_mfma_f32_16x16x32_bf16 v[62:65], v[134:137], v[188:191], v[62:65]
	v_mfma_f32_16x16x32_bf16 v[58:61], v[158:161], v[188:191], v[58:61]
	v_mfma_f32_16x16x32_bf16 v[50:53], v[134:137], v[200:203], v[50:53]
	v_mfma_f32_16x16x32_bf16 v[42:45], v[158:161], v[200:203], v[42:45]
	v_mfma_f32_16x16x32_bf16 v[34:37], v[134:137], v[208:211], v[34:37]
	v_mfma_f32_16x16x32_bf16 v[26:29], v[158:161], v[208:211], v[26:29]
	v_mfma_f32_16x16x32_bf16 v[18:21], v[134:137], v[216:219], v[18:21]
	v_mfma_f32_16x16x32_bf16 v[10:13], v[158:161], v[216:219], v[10:13]
	v_mfma_f32_16x16x32_bf16 v[54:57], v[168:171], v[184:187], v[54:57]
	v_mfma_f32_16x16x32_bf16 v[46:49], v[176:179], v[184:187], v[46:49]
	v_mfma_f32_16x16x32_bf16 v[38:41], v[168:171], v[192:195], v[38:41]
	v_mfma_f32_16x16x32_bf16 v[30:33], v[176:179], v[192:195], v[30:33]
	v_mfma_f32_16x16x32_bf16 v[22:25], v[168:171], v[204:207], v[22:25]
	v_mfma_f32_16x16x32_bf16 v[14:17], v[176:179], v[204:207], v[14:17]
	v_mfma_f32_16x16x32_bf16 v[6:9], v[168:171], v[212:215], v[6:9]
	v_mfma_f32_16x16x32_bf16 v[2:5], v[176:179], v[212:215], v[2:5]
	v_mfma_f32_16x16x32_bf16 v[54:57], v[172:175], v[188:191], v[54:57]
	v_mfma_f32_16x16x32_bf16 v[46:49], v[180:183], v[188:191], v[46:49]
	v_mfma_f32_16x16x32_bf16 v[38:41], v[172:175], v[200:203], v[38:41]
	v_mfma_f32_16x16x32_bf16 v[30:33], v[180:183], v[200:203], v[30:33]
	v_mfma_f32_16x16x32_bf16 v[22:25], v[172:175], v[208:211], v[22:25]
	v_mfma_f32_16x16x32_bf16 v[14:17], v[180:183], v[208:211], v[14:17]
	v_mfma_f32_16x16x32_bf16 v[6:9], v[172:175], v[216:219], v[6:9]
	v_mfma_f32_16x16x32_bf16 v[2:5], v[180:183], v[216:219], v[2:5]
	s_barrier
; #define PG8_STAGE(bufoff, gbase, voff) do { _Pragma("unroll") for (int _i = 0; _i < 2; ++_i) \
;         __builtin_amdgcn_global_load_lds((const unsigned*)((const char*)(gbase) + (voff)[_i]), (PG8_LAS unsigned*)(lds + (bufoff) + ldsw + _i * 8192), 16, 0, 0); } while (0)
; #define PG8_LDA(dst, b, h) do { _Pragma("unroll") for (int m = 0; m < 4; ++m) _Pragma("unroll") for (int k = 0; k < 2; ++k) dst[m][k] = *(const PG8_LAS bf16x8*)(lds + PG8_SA(b, h) + aoff + m * 2048 + k * 1024); } while (0)
; #define PG8_LDB(dst, b, h) do { _Pragma("unroll") for (int n = 0; n < 2; ++n) _Pragma("unroll") for (int k = 0; k < 2; ++k) dst[n][k] = *(const PG8_LAS bf16x8*)(lds + PG8_SB(b, h) + boff + n * 2048 + k * 1024); } while (0)
; #define PG8_MMA(ai, bj, At, Bt) do { __builtin_amdgcn_s_setprio(1); _Pragma("unroll") for (int m = 0; m < 4; ++m) _Pragma("unroll") for (int n = 0; n < 2; ++n) _Pragma("unroll") for (int k = 0; k < 2; ++k) \
;         acc[ai][bj][m][n] = __builtin_amdgcn_mfma_f32_16x16x32_bf16(Bt[n][k], At[m][k], acc[ai][bj][m][n], 0, 0, 0); __builtin_amdgcn_s_setprio(0); } while (0)
; #define PG8_WAIT_V(n) asm volatile("s_waitcnt vmcnt(" #n ")" ::: "memory")
; #define PG8_WAIT_L(n) asm volatile("s_waitcnt lgkmcnt(" #n ")" ::: "memory")
; #define PG8_BAR __builtin_amdgcn_s_barrier()
; #define PG8_SCHED __builtin_amdgcn_sched_barrier(0)
; template <class Epi, class Sched, bool ALIGN_EPI = false, bool SP2 = false>
; __device__ __forceinline__ void gemm_phase(PG8_LAS unsigned char* lds, const Gemm g, const Sched& S, const Epi& E) {
;     ...
;             PG8_LDB(B0, 1, 0); PG8_LDB(B1, 1, 1); PG8_SCHED; PG8_LDA(At, 1, 0); PG8_STAGE(PG8_SA(0, 1), a2 + hstep, voffA);
;             PG8_WAIT_V(8); PG8_WAIT_L(0); PG8_BAR; PG8_MMA(0, 0, At, B0); PG8_MMA(0, 1, At, B1); PG8_BAR; PG8_SCHED;
;             PG8_LDA(At, 1, 1); PG8_STAGE(PG8_SB(1, 0), b3, voffB); PG8_STAGE(PG8_SB(1, 1), b3 + hstep, voffB); PG8_STAGE(PG8_SA(1, 0), a3, voffA);
;             PG8_WAIT_V(8); PG8_WAIT_L(0); PG8_BAR; PG8_MMA(1, 0, At, B0); PG8_MMA(1, 1, At, B1); PG8_BAR; PG8_SCHED;
	s_setprio 0
	s_mov_b32 m0, s27
	s_nop 0
	global_load_lds_dwordx4 v138, s[34:35]
	s_mov_b32 m0, s37
	s_nop 0
	global_load_lds_dwordx4 v142, s[34:35]
	s_add_i32 s52, 0, 0x18000
	s_add_i32 s53, 0, 0x1c000
	s_add_u32 s34, s34, 0x100000
	s_addc_u32 s35, s35, 0
	s_mov_b32 m0, s38
	s_nop 0
	global_load_lds_dwordx4 v138, s[34:35]
	s_mov_b32 m0, s39
	s_nop 0
	global_load_lds_dwordx4 v142, s[34:35]
	v_add_u32_e32 v158, s52, v162
	v_add_u32_e32 v167, s53, v162
	ds_read_b128 v[130:133], v158
	ds_read_b128 v[134:137], v158 offset:1024
	ds_read_b128 v[154:157], v158 offset:2048
	ds_read_b128 v[158:161], v158 offset:3072
	ds_read_b128 v[168:171], v167
	ds_read_b128 v[172:175], v167 offset:1024
	ds_read_b128 v[176:179], v167 offset:2048
	ds_read_b128 v[180:183], v167 offset:3072
	ds_read_b128 v[184:187], v166 offset:32768
	ds_read_b128 v[188:191], v166 offset:33792
	ds_read_b128 v[192:195], v166 offset:34816
	ds_read_b128 v[200:203], v166 offset:35840
	ds_read_b128 v[204:207], v166 offset:36864
	ds_read_b128 v[208:211], v166 offset:37888
	ds_read_b128 v[212:215], v166 offset:38912
	ds_read_b128 v[216:219], v166 offset:39936
	s_waitcnt vmcnt(8)
	s_waitcnt lgkmcnt(0)
	s_setprio 1
	s_barrier
	v_mfma_f32_16x16x32_bf16 v[126:129], v[130:133], v[184:187], v[126:129]
	v_mfma_f32_16x16x32_bf16 v[122:125], v[154:157], v[184:187], v[122:125]
	v_mfma_f32_16x16x32_bf16 v[118:121], v[130:133], v[192:195], v[118:121]
	v_mfma_f32_16x16x32_bf16 v[114:117], v[154:157], v[192:195], v[114:117]
	v_mfma_f32_16x16x32_bf16 v[110:113], v[130:133], v[204:207], v[110:113]
	v_mfma_f32_16x16x32_bf16 v[102:105], v[154:157], v[204:207], v[102:105]
	v_mfma_f32_16x16x32_bf16 v[82:85], v[130:133], v[212:215], v[82:85]
	v_mfma_f32_16x16x32_bf16 v[74:77], v[154:157], v[212:215], v[74:77]
	v_mfma_f32_16x16x32_bf16 v[126:129], v[134:137], v[188:191], v[126:129]
	v_mfma_f32_16x16x32_bf16 v[122:125], v[158:161], v[188:191], v[122:125]
	v_mfma_f32_16x16x32_bf16 v[118:121], v[134:137], v[200:203], v[118:121]
	v_mfma_f32_16x16x32_bf16 v[114:117], v[158:161], v[200:203], v[114:117]
	v_mfma_f32_16x16x32_bf16 v[110:113], v[134:137], v[208:211], v[110:113]
	v_mfma_f32_16x16x32_bf16 v[102:105], v[158:161], v[208:211], v[102:105]
	v_mfma_f32_16x16x32_bf16 v[82:85], v[134:137], v[216:219], v[82:85]
	v_mfma_f32_16x16x32_bf16 v[74:77], v[158:161], v[216:219], v[74:77]
	v_mfma_f32_16x16x32_bf16 v[106:109], v[168:171], v[184:187], v[106:109]
	v_mfma_f32_16x16x32_bf16 v[98:101], v[176:179], v[184:187], v[98:101]
	v_mfma_f32_16x16x32_bf16 v[94:97], v[168:171], v[192:195], v[94:97]
	v_mfma_f32_16x16x32_bf16 v[90:93], v[176:179], v[192:195], v[90:93]
	v_mfma_f32_16x16x32_bf16 v[86:89], v[168:171], v[204:207], v[86:89]
	v_mfma_f32_16x16x32_bf16 v[78:81], v[176:179], v[204:207], v[78:81]
	v_mfma_f32_16x16x32_bf16 v[70:73], v[168:171], v[212:215], v[70:73]
	v_mfma_f32_16x16x32_bf16 v[66:69], v[176:179], v[212:215], v[66:69]
	v_mfma_f32_16x16x32_bf16 v[106:109], v[172:175], v[188:191], v[106:109]
	v_mfma_f32_16x16x32_bf16 v[98:101], v[180:183], v[188:191], v[98:101]
	v_mfma_f32_16x16x32_bf16 v[94:97], v[172:175], v[200:203], v[94:97]
	v_mfma_f32_16x16x32_bf16 v[90:93], v[180:183], v[200:203], v[90:93]
	v_mfma_f32_16x16x32_bf16 v[86:89], v[172:175], v[208:211], v[86:89]
	v_mfma_f32_16x16x32_bf16 v[78:81], v[180:183], v[208:211], v[78:81]
	v_mfma_f32_16x16x32_bf16 v[70:73], v[172:175], v[216:219], v[70:73]
	v_mfma_f32_16x16x32_bf16 v[66:69], v[180:183], v[216:219], v[66:69]
	s_barrier
	s_setprio 0
	s_add_i32 s34, s52, s36
	s_add_u32 s30, s30, 0x80
	s_addc_u32 s31, s31, 0
	s_mov_b32 m0, s34
	s_nop 0
	global_load_lds_dwordx4 v140, s[30:31]
	s_add_i32 m0, s34, 0x2000
	s_add_i32 s34, s53, s36
	global_load_lds_dwordx4 v144, s[30:31]
	s_add_u32 s30, s30, 0x100000
	s_addc_u32 s31, s31, 0
	s_mov_b32 m0, s34
	s_nop 0
	global_load_lds_dwordx4 v140, s[30:31]
	s_add_i32 m0, s34, 0x2000
	s_nop 0
	global_load_lds_dwordx4 v144, s[30:31]
	ds_read_b128 v[184:187], v166 offset:49152
	ds_read_b128 v[188:191], v166 offset:50176
	ds_read_b128 v[192:195], v166 offset:51200
	ds_read_b128 v[200:203], v166 offset:52224
	ds_read_b128 v[204:207], v166 offset:53248
	ds_read_b128 v[208:211], v166 offset:54272
	ds_read_b128 v[212:215], v166 offset:55296
	ds_read_b128 v[216:219], v166 offset:56320
	s_waitcnt vmcnt(6)
	s_waitcnt lgkmcnt(0)
	s_setprio 1
	s_barrier
	v_mfma_f32_16x16x32_bf16 v[62:65], v[130:133], v[184:187], v[62:65]
	v_mfma_f32_16x16x32_bf16 v[58:61], v[154:157], v[184:187], v[58:61]
	v_mfma_f32_16x16x32_bf16 v[50:53], v[130:133], v[192:195], v[50:53]
	v_mfma_f32_16x16x32_bf16 v[42:45], v[154:157], v[192:195], v[42:45]
	v_mfma_f32_16x16x32_bf16 v[34:37], v[130:133], v[204:207], v[34:37]
	v_mfma_f32_16x16x32_bf16 v[26:29], v[154:157], v[204:207], v[26:29]
	v_mfma_f32_16x16x32_bf16 v[18:21], v[130:133], v[212:215], v[18:21]
	v_mfma_f32_16x16x32_bf16 v[10:13], v[154:157], v[212:215], v[10:13]
	v_mfma_f32_16x16x32_bf16 v[62:65], v[134:137], v[188:191], v[62:65]
	v_mfma_f32_16x16x32_bf16 v[58:61], v[158:161], v[188:191], v[58:61]
	v_mfma_f32_16x16x32_bf16 v[50:53], v[134:137], v[200:203], v[50:53]
	v_mfma_f32_16x16x32_bf16 v[42:45], v[158:161], v[200:203], v[42:45]
	v_mfma_f32_16x16x32_bf16 v[34:37], v[134:137], v[208:211], v[34:37]
	v_mfma_f32_16x16x32_bf16 v[26:29], v[158:161], v[208:211], v[26:29]
	v_mfma_f32_16x16x32_bf16 v[18:21], v[134:137], v[216:219], v[18:21]
	v_mfma_f32_16x16x32_bf16 v[10:13], v[158:161], v[216:219], v[10:13]
	v_mfma_f32_16x16x32_bf16 v[54:57], v[168:171], v[184:187], v[54:57]
	v_mfma_f32_16x16x32_bf16 v[46:49], v[176:179], v[184:187], v[46:49]
	v_mfma_f32_16x16x32_bf16 v[38:41], v[168:171], v[192:195], v[38:41]
	v_mfma_f32_16x16x32_bf16 v[30:33], v[176:179], v[192:195], v[30:33]
	v_mfma_f32_16x16x32_bf16 v[22:25], v[168:171], v[204:207], v[22:25]
	v_mfma_f32_16x16x32_bf16 v[14:17], v[176:179], v[204:207], v[14:17]
	v_mfma_f32_16x16x32_bf16 v[6:9], v[168:171], v[212:215], v[6:9]
	v_mfma_f32_16x16x32_bf16 v[2:5], v[176:179], v[212:215], v[2:5]
	v_mfma_f32_16x16x32_bf16 v[54:57], v[172:175], v[188:191], v[54:57]
	v_mfma_f32_16x16x32_bf16 v[46:49], v[180:183], v[188:191], v[46:49]
	v_mfma_f32_16x16x32_bf16 v[38:41], v[172:175], v[200:203], v[38:41]
	v_mfma_f32_16x16x32_bf16 v[30:33], v[180:183], v[200:203], v[30:33]
	v_mfma_f32_16x16x32_bf16 v[22:25], v[172:175], v[208:211], v[22:25]
	v_mfma_f32_16x16x32_bf16 v[14:17], v[180:183], v[208:211], v[14:17]
	v_mfma_f32_16x16x32_bf16 v[6:9], v[172:175], v[216:219], v[6:9]
	v_mfma_f32_16x16x32_bf16 v[2:5], v[180:183], v[216:219], v[2:5]
	s_barrier
	s_setprio 0
	s_add_i32 s51, s51, 2
	s_add_u32 s28, s28, 0x100
	s_addc_u32 s29, s29, 0
	s_add_u32 s49, s49, 0x100
	s_addc_u32 s50, s50, 0
	s_cmp_gt_u32 s51, 61
	s_cbranch_scc0 .LBB0_959
	s_and_b64 vcc, exec, s[8:9]
	s_cbranch_vccz .LBB0_962
	s_barrier

; #define PG8_STAGE(bufoff, gbase, voff) do { _Pragma("unroll") for (int _i = 0; _i < 2; ++_i) \
;         __builtin_amdgcn_global_load_lds((const unsigned*)((const char*)(gbase) + (voff)[_i]), (PG8_LAS unsigned*)(lds + (bufoff) + ldsw + _i * 8192), 16, 0, 0); } while (0)
; #define PG8_LDA(dst, b, h) do { _Pragma("unroll") for (int m = 0; m < 4; ++m) _Pragma("unroll") for (int k = 0; k < 2; ++k) dst[m][k] = *(const PG8_LAS bf16x8*)(lds + PG8_SA(b, h) + aoff + m * 2048 + k * 1024); } while (0)
; #define PG8_LDB(dst, b, h) do { _Pragma("unroll") for (int n = 0; n < 2; ++n) _Pragma("unroll") for (int k = 0; k < 2; ++k) dst[n][k] = *(const PG8_LAS bf16x8*)(lds + PG8_SB(b, h) + boff + n * 2048 + k * 1024); } while (0)
; #define PG8_WAIT_V(n) asm volatile("s_waitcnt vmcnt(" #n ")" ::: "memory")
; #define PG8_WAIT_L(n) asm volatile("s_waitcnt lgkmcnt(" #n ")" ::: "memory")
; #define PG8_BAR __builtin_amdgcn_s_barrier()
; #define PG8_SCHED __builtin_amdgcn_sched_barrier(0)
; template <class Epi, class Sched, bool ALIGN_EPI = false, bool SP2 = false>
; __device__ __forceinline__ void gemm_phase(PG8_LAS unsigned char* lds, const Gemm g, const Sched& S, const Epi& E) {
;     ...
;         for (int t = 0; t < nt; t += 2) {
;             const bool last = (t == nt - 2);
;             const char* a1 = cA + (size_t)(t + 1) * kstep;
;             const char* a2 = last ? nA : cA + (size_t)(t + 2) * kstep; const char* b2 = last ? nB : cB + (size_t)(t + 2) * kstep;
;             const char* a3 = a2 + kstep; const char* b3 = b2 + kstep;
;             if (last && has_next) S.a_ready(nxt);
;             if constexpr (SP2) {
;             PG8_LDB(B0, 0, 0); PG8_LDB(B1, 0, 1); PG8_SCHED; PG8_LDA(At, 0, 0); PG8_STAGE(PG8_SA(1, 1), a1 + hstep, voffA);
;             PG8_WAIT_V(8); PG8_WAIT_L(0); PG8_BAR; PG8_MMA(0, 0, At, B0); PG8_MMA(0, 1, At, B1); PG8_BAR; PG8_SCHED;
;             PG8_LDA(At, 0, 1); PG8_STAGE(PG8_SB(0, 0), b2, voffB); PG8_STAGE(PG8_SB(0, 1), b2 + hstep, voffB); PG8_STAGE(PG8_SA(0, 0), a2, voffA);
;             PG8_WAIT_V(8); PG8_WAIT_L(0); PG8_BAR; PG8_MMA(1, 0, At, B0); PG8_MMA(1, 1, At, B1); PG8_BAR; PG8_SCHED;
;             PG8_LDB(B0, 1, 0); PG8_LDB(B1, 1, 1); PG8_SCHED; PG8_LDA(At, 1, 0); PG8_STAGE(PG8_SA(0, 1), a2 + hstep, voffA);
;             PG8_WAIT_V(8); PG8_WAIT_L(0); PG8_BAR; PG8_MMA(0, 0, At, B0); PG8_MMA(0, 1, At, B1); PG8_BAR; PG8_SCHED;
.LBB0_1081:
	s_add_u32 s34, s30, 0xfff00000
	s_addc_u32 s35, s31, -1
	s_mov_b32 m0, s44
	s_nop 0
	global_load_lds_dwordx4 v136, s[34:35]
	s_mov_b32 m0, s45
	s_nop 0
	global_load_lds_dwordx4 v132, s[34:35]
	s_add_u32 s34, s34, 0x80
	s_addc_u32 s35, s35, 0
	s_cmp_eq_u32 s55, 60
	s_cselect_b32 s37, s15, s35
	s_cselect_b32 s36, s51, s34
	s_cselect_b32 s35, s13, s54
	s_cselect_b32 s34, s52, s53
	s_add_i32 m0, s29, 0xc000
	s_nop 0
	global_load_lds_dwordx4 v138, s[30:31]
	s_add_i32 m0, s29, 0xe000
	s_nop 0
	global_load_lds_dwordx4 v140, s[30:31]
	ds_read_b128 v[154:157], v150
	ds_read_b128 v[158:161], v150 offset:1024
	ds_read_b128 v[162:165], v150 offset:2048
	ds_read_b128 v[166:169], v150 offset:3072
	ds_read_b128 v[170:173], v151
	ds_read_b128 v[174:177], v151 offset:1024
	ds_read_b128 v[178:181], v151 offset:2048
	ds_read_b128 v[182:185], v151 offset:3072
	ds_read_b128 v[186:189], v152
	ds_read_b128 v[190:193], v152 offset:1024
	ds_read_b128 v[194:197], v152 offset:2048
	ds_read_b128 v[200:203], v152 offset:3072
	ds_read_b128 v[204:207], v152 offset:4096
	ds_read_b128 v[208:211], v152 offset:5120
	ds_read_b128 v[212:215], v152 offset:6144
	ds_read_b128 v[216:219], v152 offset:7168
	s_waitcnt vmcnt(8)
	s_waitcnt lgkmcnt(0)
	s_setprio 1
	s_barrier
	v_mfma_f32_16x16x32_bf16 v[126:129], v[154:157], v[186:189], v[126:129]
	v_mfma_f32_16x16x32_bf16 v[122:125], v[162:165], v[186:189], v[122:125]
	v_mfma_f32_16x16x32_bf16 v[110:113], v[154:157], v[194:197], v[110:113]
	v_mfma_f32_16x16x32_bf16 v[106:109], v[162:165], v[194:197], v[106:109]
	v_mfma_f32_16x16x32_bf16 v[94:97], v[154:157], v[204:207], v[94:97]
	v_mfma_f32_16x16x32_bf16 v[90:93], v[162:165], v[204:207], v[90:93]
	v_mfma_f32_16x16x32_bf16 v[78:81], v[154:157], v[212:215], v[78:81]
	v_mfma_f32_16x16x32_bf16 v[74:77], v[162:165], v[212:215], v[74:77]
	v_mfma_f32_16x16x32_bf16 v[126:129], v[158:161], v[190:193], v[126:129]
	v_mfma_f32_16x16x32_bf16 v[122:125], v[166:169], v[190:193], v[122:125]
	v_mfma_f32_16x16x32_bf16 v[110:113], v[158:161], v[200:203], v[110:113]
	v_mfma_f32_16x16x32_bf16 v[106:109], v[166:169], v[200:203], v[106:109]
	v_mfma_f32_16x16x32_bf16 v[94:97], v[158:161], v[208:211], v[94:97]
	v_mfma_f32_16x16x32_bf16 v[90:93], v[166:169], v[208:211], v[90:93]
	v_mfma_f32_16x16x32_bf16 v[78:81], v[158:161], v[216:219], v[78:81]
	v_mfma_f32_16x16x32_bf16 v[74:77], v[166:169], v[216:219], v[74:77]
	v_mfma_f32_16x16x32_bf16 v[118:121], v[170:173], v[186:189], v[118:121]
	v_mfma_f32_16x16x32_bf16 v[114:117], v[178:181], v[186:189], v[114:117]
	v_mfma_f32_16x16x32_bf16 v[102:105], v[170:173], v[194:197], v[102:105]
	v_mfma_f32_16x16x32_bf16 v[98:101], v[178:181], v[194:197], v[98:101]
	v_mfma_f32_16x16x32_bf16 v[86:89], v[170:173], v[204:207], v[86:89]
	v_mfma_f32_16x16x32_bf16 v[82:85], v[178:181], v[204:207], v[82:85]
	v_mfma_f32_16x16x32_bf16 v[70:73], v[170:173], v[212:215], v[70:73]
	v_mfma_f32_16x16x32_bf16 v[66:69], v[178:181], v[212:215], v[66:69]
	v_mfma_f32_16x16x32_bf16 v[118:121], v[174:177], v[190:193], v[118:121]
	v_mfma_f32_16x16x32_bf16 v[114:117], v[182:185], v[190:193], v[114:117]
	v_mfma_f32_16x16x32_bf16 v[102:105], v[174:177], v[200:203], v[102:105]
	v_mfma_f32_16x16x32_bf16 v[98:101], v[182:185], v[200:203], v[98:101]
	v_mfma_f32_16x16x32_bf16 v[86:89], v[174:177], v[208:211], v[86:89]
	v_mfma_f32_16x16x32_bf16 v[82:85], v[182:185], v[208:211], v[82:85]
	v_mfma_f32_16x16x32_bf16 v[70:73], v[174:177], v[216:219], v[70:73]
	v_mfma_f32_16x16x32_bf16 v[66:69], v[182:185], v[216:219], v[66:69]
	s_barrier
	s_setprio 0
	s_add_i32 s56, s47, s33
	s_mov_b32 m0, s56
	s_nop 0
	global_load_lds_dwordx4 v134, s[34:35]
	s_add_i32 m0, s56, 0x2000
	s_add_u32 s56, s34, 0x100000
	s_addc_u32 s57, s35, 0
	s_add_i32 s58, s48, s33
	global_load_lds_dwordx4 v130, s[34:35]
	s_mov_b32 m0, s58
	s_nop 0
	global_load_lds_dwordx4 v134, s[56:57]
	s_add_i32 m0, s58, 0x2000
	s_nop 0
	global_load_lds_dwordx4 v130, s[56:57]
	ds_read_b128 v[186:189], v152 offset:16384
	ds_read_b128 v[190:193], v152 offset:17408
	ds_read_b128 v[194:197], v152 offset:18432
	ds_read_b128 v[200:203], v152 offset:19456
	ds_read_b128 v[204:207], v152 offset:20480
	ds_read_b128 v[208:211], v152 offset:21504
	ds_read_b128 v[212:215], v152 offset:22528
	ds_read_b128 v[216:219], v152 offset:23552
	s_waitcnt vmcnt(6)
	s_waitcnt lgkmcnt(0)
	s_setprio 1
	s_barrier
	v_mfma_f32_16x16x32_bf16 v[62:65], v[154:157], v[186:189], v[62:65]
	v_mfma_f32_16x16x32_bf16 v[58:61], v[162:165], v[186:189], v[58:61]
	v_mfma_f32_16x16x32_bf16 v[46:49], v[154:157], v[194:197], v[46:49]
	v_mfma_f32_16x16x32_bf16 v[42:45], v[162:165], v[194:197], v[42:45]
	v_mfma_f32_16x16x32_bf16 v[30:33], v[154:157], v[204:207], v[30:33]
	v_mfma_f32_16x16x32_bf16 v[26:29], v[162:165], v[204:207], v[26:29]
	v_mfma_f32_16x16x32_bf16 v[14:17], v[154:157], v[212:215], v[14:17]
	v_mfma_f32_16x16x32_bf16 v[10:13], v[162:165], v[212:215], v[10:13]
	v_mfma_f32_16x16x32_bf16 v[62:65], v[158:161], v[190:193], v[62:65]
	v_mfma_f32_16x16x32_bf16 v[58:61], v[166:169], v[190:193], v[58:61]
	v_mfma_f32_16x16x32_bf16 v[46:49], v[158:161], v[200:203], v[46:49]
	v_mfma_f32_16x16x32_bf16 v[42:45], v[166:169], v[200:203], v[42:45]
	v_mfma_f32_16x16x32_bf16 v[30:33], v[158:161], v[208:211], v[30:33]
	v_mfma_f32_16x16x32_bf16 v[26:29], v[166:169], v[208:211], v[26:29]
	v_mfma_f32_16x16x32_bf16 v[14:17], v[158:161], v[216:219], v[14:17]
	v_mfma_f32_16x16x32_bf16 v[10:13], v[166:169], v[216:219], v[10:13]
	v_mfma_f32_16x16x32_bf16 v[54:57], v[170:173], v[186:189], v[54:57]
	v_mfma_f32_16x16x32_bf16 v[50:53], v[178:181], v[186:189], v[50:53]
	v_mfma_f32_16x16x32_bf16 v[38:41], v[170:173], v[194:197], v[38:41]
	v_mfma_f32_16x16x32_bf16 v[34:37], v[178:181], v[194:197], v[34:37]
	v_mfma_f32_16x16x32_bf16 v[22:25], v[170:173], v[204:207], v[22:25]
	v_mfma_f32_16x16x32_bf16 v[18:21], v[178:181], v[204:207], v[18:21]
	v_mfma_f32_16x16x32_bf16 v[6:9], v[170:173], v[212:215], v[6:9]
	v_mfma_f32_16x16x32_bf16 v[2:5], v[178:181], v[212:215], v[2:5]
	v_mfma_f32_16x16x32_bf16 v[54:57], v[174:177], v[190:193], v[54:57]
	v_mfma_f32_16x16x32_bf16 v[50:53], v[182:185], v[190:193], v[50:53]
	v_mfma_f32_16x16x32_bf16 v[38:41], v[174:177], v[200:203], v[38:41]
	v_mfma_f32_16x16x32_bf16 v[34:37], v[182:185], v[200:203], v[34:37]
	v_mfma_f32_16x16x32_bf16 v[22:25], v[174:177], v[208:211], v[22:25]
	v_mfma_f32_16x16x32_bf16 v[18:21], v[182:185], v[208:211], v[18:21]
	v_mfma_f32_16x16x32_bf16 v[6:9], v[174:177], v[216:219], v[6:9]
	v_mfma_f32_16x16x32_bf16 v[2:5], v[182:185], v[216:219], v[2:5]
	s_barrier
; #define PG8_STAGE(bufoff, gbase, voff) do { _Pragma("unroll") for (int _i = 0; _i < 2; ++_i) \
;         __builtin_amdgcn_global_load_lds((const unsigned*)((const char*)(gbase) + (voff)[_i]), (PG8_LAS unsigned*)(lds + (bufoff) + ldsw + _i * 8192), 16, 0, 0); } while (0)
; #define PG8_LDA(dst, b, h) do { _Pragma("unroll") for (int m = 0; m < 4; ++m) _Pragma("unroll") for (int k = 0; k < 2; ++k) dst[m][k] = *(const PG8_LAS bf16x8*)(lds + PG8_SA(b, h) + aoff + m * 2048 + k * 1024); } while (0)
; #define PG8_LDB(dst, b, h) do { _Pragma("unroll") for (int n = 0; n < 2; ++n) _Pragma("unroll") for (int k = 0; k < 2; ++k) dst[n][k] = *(const PG8_LAS bf16x8*)(lds + PG8_SB(b, h) + boff + n * 2048 + k * 1024); } while (0)
; #define PG8_MMA(ai, bj, At, Bt) do { __builtin_amdgcn_s_setprio(1); _Pragma("unroll") for (int m = 0; m < 4; ++m) _Pragma("unroll") for (int n = 0; n < 2; ++n) _Pragma("unroll") for (int k = 0; k < 2; ++k) \
;         acc[ai][bj][m][n] = __builtin_amdgcn_mfma_f32_16x16x32_bf16(Bt[n][k], At[m][k], acc[ai][bj][m][n], 0, 0, 0); __builtin_amdgcn_s_setprio(0); } while (0)
; #define PG8_WAIT_V(n) asm volatile("s_waitcnt vmcnt(" #n ")" ::: "memory")
; #define PG8_WAIT_L(n) asm volatile("s_waitcnt lgkmcnt(" #n ")" ::: "memory")
; #define PG8_BAR __builtin_amdgcn_s_barrier()
; #define PG8_SCHED __builtin_amdgcn_sched_barrier(0)
; template <class Epi, class Sched, bool ALIGN_EPI = false, bool SP2 = false>
; __device__ __forceinline__ void gemm_phase(PG8_LAS unsigned char* lds, const Gemm g, const Sched& S, const Epi& E) {
;     ...
;             PG8_LDB(B0, 1, 0); PG8_LDB(B1, 1, 1); PG8_SCHED; PG8_LDA(At, 1, 0); PG8_STAGE(PG8_SA(0, 1), a2 + hstep, voffA);
;             PG8_WAIT_V(8); PG8_WAIT_L(0); PG8_BAR; PG8_MMA(0, 0, At, B0); PG8_MMA(0, 1, At, B1); PG8_BAR; PG8_SCHED;
;             PG8_LDA(At, 1, 1); PG8_STAGE(PG8_SB(1, 0), b3, voffB); PG8_STAGE(PG8_SB(1, 1), b3 + hstep, voffB); PG8_STAGE(PG8_SA(1, 0), a3, voffA);
;             PG8_WAIT_V(8); PG8_WAIT_L(0); PG8_BAR; PG8_MMA(1, 0, At, B0); PG8_MMA(1, 1, At, B1); PG8_BAR; PG8_SCHED;
	s_setprio 0
	s_mov_b32 m0, s29
	s_nop 0
	global_load_lds_dwordx4 v136, s[36:37]
	s_mov_b32 m0, s40
	s_nop 0
	global_load_lds_dwordx4 v132, s[36:37]
	s_add_i32 s56, 0, 0x18000
	s_add_i32 s57, 0, 0x1c000
	s_add_u32 s36, s36, 0x100000
	s_addc_u32 s37, s37, 0
	s_mov_b32 m0, s41
	s_nop 0
	global_load_lds_dwordx4 v136, s[36:37]
	s_mov_b32 m0, s42
	s_nop 0
	global_load_lds_dwordx4 v132, s[36:37]
	v_add_u32_e32 v153, s56, v148
	ds_read_b128 v[154:157], v153
	ds_read_b128 v[158:161], v153 offset:1024
	ds_read_b128 v[162:165], v153 offset:2048
	ds_read_b128 v[166:169], v153 offset:3072
	v_add_u32_e32 v153, s57, v148
	ds_read_b128 v[170:173], v153
	ds_read_b128 v[174:177], v153 offset:1024
	ds_read_b128 v[178:181], v153 offset:2048
	ds_read_b128 v[182:185], v153 offset:3072
	ds_read_b128 v[186:189], v152 offset:32768
	ds_read_b128 v[190:193], v152 offset:33792
	ds_read_b128 v[194:197], v152 offset:34816
	ds_read_b128 v[200:203], v152 offset:35840
	ds_read_b128 v[204:207], v152 offset:36864
	ds_read_b128 v[208:211], v152 offset:37888
	ds_read_b128 v[212:215], v152 offset:38912
	ds_read_b128 v[216:219], v152 offset:39936
	s_waitcnt vmcnt(8)
	s_waitcnt lgkmcnt(0)
	s_setprio 1
	s_barrier
	v_mfma_f32_16x16x32_bf16 v[126:129], v[154:157], v[186:189], v[126:129]
	v_mfma_f32_16x16x32_bf16 v[122:125], v[162:165], v[186:189], v[122:125]
	v_mfma_f32_16x16x32_bf16 v[110:113], v[154:157], v[194:197], v[110:113]
	v_mfma_f32_16x16x32_bf16 v[106:109], v[162:165], v[194:197], v[106:109]
	v_mfma_f32_16x16x32_bf16 v[94:97], v[154:157], v[204:207], v[94:97]
	v_mfma_f32_16x16x32_bf16 v[90:93], v[162:165], v[204:207], v[90:93]
	v_mfma_f32_16x16x32_bf16 v[78:81], v[154:157], v[212:215], v[78:81]
	v_mfma_f32_16x16x32_bf16 v[74:77], v[162:165], v[212:215], v[74:77]
	v_mfma_f32_16x16x32_bf16 v[126:129], v[158:161], v[190:193], v[126:129]
	v_mfma_f32_16x16x32_bf16 v[122:125], v[166:169], v[190:193], v[122:125]
	v_mfma_f32_16x16x32_bf16 v[110:113], v[158:161], v[200:203], v[110:113]
	v_mfma_f32_16x16x32_bf16 v[106:109], v[166:169], v[200:203], v[106:109]
	v_mfma_f32_16x16x32_bf16 v[94:97], v[158:161], v[208:211], v[94:97]
	v_mfma_f32_16x16x32_bf16 v[90:93], v[166:169], v[208:211], v[90:93]
	v_mfma_f32_16x16x32_bf16 v[78:81], v[158:161], v[216:219], v[78:81]
	v_mfma_f32_16x16x32_bf16 v[74:77], v[166:169], v[216:219], v[74:77]
	v_mfma_f32_16x16x32_bf16 v[118:121], v[170:173], v[186:189], v[118:121]
	v_mfma_f32_16x16x32_bf16 v[114:117], v[178:181], v[186:189], v[114:117]
	v_mfma_f32_16x16x32_bf16 v[102:105], v[170:173], v[194:197], v[102:105]
	v_mfma_f32_16x16x32_bf16 v[98:101], v[178:181], v[194:197], v[98:101]
	v_mfma_f32_16x16x32_bf16 v[86:89], v[170:173], v[204:207], v[86:89]
	v_mfma_f32_16x16x32_bf16 v[82:85], v[178:181], v[204:207], v[82:85]
	v_mfma_f32_16x16x32_bf16 v[70:73], v[170:173], v[212:215], v[70:73]
	v_mfma_f32_16x16x32_bf16 v[66:69], v[178:181], v[212:215], v[66:69]
	v_mfma_f32_16x16x32_bf16 v[118:121], v[174:177], v[190:193], v[118:121]
	v_mfma_f32_16x16x32_bf16 v[114:117], v[182:185], v[190:193], v[114:117]
	v_mfma_f32_16x16x32_bf16 v[102:105], v[174:177], v[200:203], v[102:105]
	v_mfma_f32_16x16x32_bf16 v[98:101], v[182:185], v[200:203], v[98:101]
	v_mfma_f32_16x16x32_bf16 v[86:89], v[174:177], v[208:211], v[86:89]
	v_mfma_f32_16x16x32_bf16 v[82:85], v[182:185], v[208:211], v[82:85]
	v_mfma_f32_16x16x32_bf16 v[70:73], v[174:177], v[216:219], v[70:73]
	v_mfma_f32_16x16x32_bf16 v[66:69], v[182:185], v[216:219], v[66:69]
	s_barrier
	s_setprio 0
	s_add_i32 s36, s56, s33
	s_add_u32 s34, s34, 0x80
	s_addc_u32 s35, s35, 0
	s_mov_b32 m0, s36
	s_nop 0
	global_load_lds_dwordx4 v134, s[34:35]
	s_add_i32 m0, s36, 0x2000
	s_add_i32 s36, s57, s33
	global_load_lds_dwordx4 v130, s[34:35]
	s_add_u32 s34, s34, 0x100000
	s_addc_u32 s35, s35, 0
	s_mov_b32 m0, s36
	s_nop 0
	global_load_lds_dwordx4 v134, s[34:35]
	s_add_i32 m0, s36, 0x2000
	s_nop 0
	global_load_lds_dwordx4 v130, s[34:35]
	ds_read_b128 v[186:189], v152 offset:49152
	ds_read_b128 v[190:193], v152 offset:50176
	ds_read_b128 v[194:197], v152 offset:51200
	ds_read_b128 v[200:203], v152 offset:52224
	ds_read_b128 v[204:207], v152 offset:53248
	ds_read_b128 v[208:211], v152 offset:54272
	ds_read_b128 v[212:215], v152 offset:55296
	ds_read_b128 v[216:219], v152 offset:56320
	s_waitcnt vmcnt(6)
	s_waitcnt lgkmcnt(0)
	s_setprio 1
	s_barrier
	v_mfma_f32_16x16x32_bf16 v[62:65], v[154:157], v[186:189], v[62:65]
	v_mfma_f32_16x16x32_bf16 v[58:61], v[162:165], v[186:189], v[58:61]
	v_mfma_f32_16x16x32_bf16 v[46:49], v[154:157], v[194:197], v[46:49]
	v_mfma_f32_16x16x32_bf16 v[42:45], v[162:165], v[194:197], v[42:45]
	v_mfma_f32_16x16x32_bf16 v[30:33], v[154:157], v[204:207], v[30:33]
	v_mfma_f32_16x16x32_bf16 v[26:29], v[162:165], v[204:207], v[26:29]
	v_mfma_f32_16x16x32_bf16 v[14:17], v[154:157], v[212:215], v[14:17]
	v_mfma_f32_16x16x32_bf16 v[10:13], v[162:165], v[212:215], v[10:13]
	v_mfma_f32_16x16x32_bf16 v[62:65], v[158:161], v[190:193], v[62:65]
	v_mfma_f32_16x16x32_bf16 v[58:61], v[166:169], v[190:193], v[58:61]
	v_mfma_f32_16x16x32_bf16 v[46:49], v[158:161], v[200:203], v[46:49]
	v_mfma_f32_16x16x32_bf16 v[42:45], v[166:169], v[200:203], v[42:45]
	v_mfma_f32_16x16x32_bf16 v[30:33], v[158:161], v[208:211], v[30:33]
	v_mfma_f32_16x16x32_bf16 v[26:29], v[166:169], v[208:211], v[26:29]
	v_mfma_f32_16x16x32_bf16 v[14:17], v[158:161], v[216:219], v[14:17]
	v_mfma_f32_16x16x32_bf16 v[10:13], v[166:169], v[216:219], v[10:13]
	v_mfma_f32_16x16x32_bf16 v[54:57], v[170:173], v[186:189], v[54:57]
	v_mfma_f32_16x16x32_bf16 v[50:53], v[178:181], v[186:189], v[50:53]
	v_mfma_f32_16x16x32_bf16 v[38:41], v[170:173], v[194:197], v[38:41]
	v_mfma_f32_16x16x32_bf16 v[34:37], v[178:181], v[194:197], v[34:37]
	v_mfma_f32_16x16x32_bf16 v[22:25], v[170:173], v[204:207], v[22:25]
	v_mfma_f32_16x16x32_bf16 v[18:21], v[178:181], v[204:207], v[18:21]
	v_mfma_f32_16x16x32_bf16 v[6:9], v[170:173], v[212:215], v[6:9]
	v_mfma_f32_16x16x32_bf16 v[2:5], v[178:181], v[212:215], v[2:5]
	v_mfma_f32_16x16x32_bf16 v[54:57], v[174:177], v[190:193], v[54:57]
	v_mfma_f32_16x16x32_bf16 v[50:53], v[182:185], v[190:193], v[50:53]
	v_mfma_f32_16x16x32_bf16 v[38:41], v[174:177], v[200:203], v[38:41]
	v_mfma_f32_16x16x32_bf16 v[34:37], v[182:185], v[200:203], v[34:37]
	v_mfma_f32_16x16x32_bf16 v[22:25], v[174:177], v[208:211], v[22:25]
	v_mfma_f32_16x16x32_bf16 v[18:21], v[182:185], v[208:211], v[18:21]
	v_mfma_f32_16x16x32_bf16 v[6:9], v[174:177], v[216:219], v[6:9]
	v_mfma_f32_16x16x32_bf16 v[2:5], v[182:185], v[216:219], v[2:5]
	s_barrier
	s_setprio 0
	s_add_i32 s55, s55, 2
	s_add_u32 s30, s30, 0x100
	s_addc_u32 s31, s31, 0
	s_add_u32 s53, s53, 0x100
	s_addc_u32 s54, s54, 0
	s_cmp_gt_u32 s55, 61
	s_cbranch_scc0 .LBB0_1081
	s_and_b64 vcc, exec, s[10:11]
	s_cbranch_vccz .LBB0_1084
	s_barrier

; #define PG8_STAGE(bufoff, gbase, voff) do { _Pragma("unroll") for (int _i = 0; _i < 2; ++_i) \
;         __builtin_amdgcn_global_load_lds((const unsigned*)((const char*)(gbase) + (voff)[_i]), (PG8_LAS unsigned*)(lds + (bufoff) + ldsw + _i * 8192), 16, 0, 0); } while (0)
; #define PG8_LDA(dst, b, h) do { _Pragma("unroll") for (int m = 0; m < 4; ++m) _Pragma("unroll") for (int k = 0; k < 2; ++k) dst[m][k] = *(const PG8_LAS bf16x8*)(lds + PG8_SA(b, h) + aoff + m * 2048 + k * 1024); } while (0)
; #define PG8_LDB(dst, b, h) do { _Pragma("unroll") for (int n = 0; n < 2; ++n) _Pragma("unroll") for (int k = 0; k < 2; ++k) dst[n][k] = *(const PG8_LAS bf16x8*)(lds + PG8_SB(b, h) + boff + n * 2048 + k * 1024); } while (0)
; #define PG8_WAIT_V(n) asm volatile("s_waitcnt vmcnt(" #n ")" ::: "memory")
; #define PG8_WAIT_L(n) asm volatile("s_waitcnt lgkmcnt(" #n ")" ::: "memory")
; #define PG8_BAR __builtin_amdgcn_s_barrier()
; #define PG8_SCHED __builtin_amdgcn_sched_barrier(0)
; template <class Epi, class Sched, bool ALIGN_EPI = false, bool SP2 = false>
; __device__ __forceinline__ void gemm_phase(PG8_LAS unsigned char* lds, const Gemm g, const Sched& S, const Epi& E) {
;     ...
;         for (int t = 0; t < nt; t += 2) {
;             const bool last = (t == nt - 2);
;             const char* a1 = cA + (size_t)(t + 1) * kstep;
;             const char* a2 = last ? nA : cA + (size_t)(t + 2) * kstep; const char* b2 = last ? nB : cB + (size_t)(t + 2) * kstep;
;             const char* a3 = a2 + kstep; const char* b3 = b2 + kstep;
;             if (last && has_next) S.a_ready(nxt);
;             if constexpr (SP2) {
;             PG8_LDB(B0, 0, 0); PG8_LDB(B1, 0, 1); PG8_SCHED; PG8_LDA(At, 0, 0); PG8_STAGE(PG8_SA(1, 1), a1 + hstep, voffA);
;             PG8_WAIT_V(8); PG8_WAIT_L(0); PG8_BAR; PG8_MMA(0, 0, At, B0); PG8_MMA(0, 1, At, B1); PG8_BAR; PG8_SCHED;
;             PG8_LDA(At, 0, 1); PG8_STAGE(PG8_SB(0, 0), b2, voffB); PG8_STAGE(PG8_SB(0, 1), b2 + hstep, voffB); PG8_STAGE(PG8_SA(0, 0), a2, voffA);
;             PG8_WAIT_V(8); PG8_WAIT_L(0); PG8_BAR; PG8_MMA(1, 0, At, B0); PG8_MMA(1, 1, At, B1); PG8_BAR; PG8_SCHED;
;             PG8_LDB(B0, 1, 0); PG8_LDB(B1, 1, 1); PG8_SCHED; PG8_LDA(At, 1, 0); PG8_STAGE(PG8_SA(0, 1), a2 + hstep, voffA);
;             PG8_WAIT_V(8); PG8_WAIT_L(0); PG8_BAR; PG8_MMA(0, 0, At, B0); PG8_MMA(0, 1, At, B1); PG8_BAR; PG8_SCHED;
.LBB0_1164:
	s_add_u32 s16, s14, 0xffd50000
	s_addc_u32 s17, s15, -1
	s_mov_b32 m0, s29
	s_nop 0
	global_load_lds_dwordx4 v128, s[16:17]
	s_mov_b32 m0, s30
	s_nop 0
	global_load_lds_dwordx4 v130, s[16:17]
	s_add_u32 s16, s16, 0x80
	s_addc_u32 s17, s17, 0
	s_cmpk_eq_i32 s41, 0xa8
	s_cselect_b32 s21, s5, s17
	s_cselect_b32 s20, s4, s16
	s_cselect_b32 s17, s13, s40
	s_cselect_b32 s16, s12, s39
	s_add_i32 m0, s24, 0xc000
	s_nop 0
	global_load_lds_dwordx4 v132, s[14:15]
	s_add_i32 m0, s24, 0xe000
	s_nop 0
	global_load_lds_dwordx4 v134, s[14:15]
	ds_read_b128 v[140:143], v193
	ds_read_b128 v[144:147], v193 offset:1024
	ds_read_b128 v[148:151], v193 offset:2048
	ds_read_b128 v[152:155], v193 offset:3072
	ds_read_b128 v[156:159], v194
	ds_read_b128 v[160:163], v194 offset:1024
	ds_read_b128 v[164:167], v194 offset:2048
	ds_read_b128 v[168:171], v194 offset:3072
	ds_read_b128 v[172:175], v195
	ds_read_b128 v[176:179], v195 offset:1024
	ds_read_b128 v[180:183], v195 offset:2048
	ds_read_b128 v[184:187], v195 offset:3072
	ds_read_b128 v[196:199], v195 offset:4096
	ds_read_b128 v[200:203], v195 offset:5120
	ds_read_b128 v[204:207], v195 offset:6144
	ds_read_b128 v[208:211], v195 offset:7168
	s_waitcnt vmcnt(8)
	s_waitcnt lgkmcnt(0)
	s_setprio 1
	s_barrier
	v_mfma_f32_16x16x32_bf16 v[124:127], v[140:143], v[172:175], v[124:127]
	v_mfma_f32_16x16x32_bf16 v[120:123], v[148:151], v[172:175], v[120:123]
	v_mfma_f32_16x16x32_bf16 v[112:115], v[140:143], v[180:183], v[112:115]
	v_mfma_f32_16x16x32_bf16 v[104:107], v[148:151], v[180:183], v[104:107]
	v_mfma_f32_16x16x32_bf16 v[96:99], v[140:143], v[196:199], v[96:99]
	v_mfma_f32_16x16x32_bf16 v[88:91], v[148:151], v[196:199], v[88:91]
	v_mfma_f32_16x16x32_bf16 v[80:83], v[140:143], v[204:207], v[80:83]
	v_mfma_f32_16x16x32_bf16 v[72:75], v[148:151], v[204:207], v[72:75]
	v_mfma_f32_16x16x32_bf16 v[124:127], v[144:147], v[176:179], v[124:127]
	v_mfma_f32_16x16x32_bf16 v[120:123], v[152:155], v[176:179], v[120:123]
	v_mfma_f32_16x16x32_bf16 v[112:115], v[144:147], v[184:187], v[112:115]
	v_mfma_f32_16x16x32_bf16 v[104:107], v[152:155], v[184:187], v[104:107]
	v_mfma_f32_16x16x32_bf16 v[96:99], v[144:147], v[200:203], v[96:99]
	v_mfma_f32_16x16x32_bf16 v[88:91], v[152:155], v[200:203], v[88:91]
	v_mfma_f32_16x16x32_bf16 v[80:83], v[144:147], v[208:211], v[80:83]
	v_mfma_f32_16x16x32_bf16 v[72:75], v[152:155], v[208:211], v[72:75]
	v_mfma_f32_16x16x32_bf16 v[116:119], v[156:159], v[172:175], v[116:119]
	v_mfma_f32_16x16x32_bf16 v[108:111], v[164:167], v[172:175], v[108:111]
	v_mfma_f32_16x16x32_bf16 v[100:103], v[156:159], v[180:183], v[100:103]
	v_mfma_f32_16x16x32_bf16 v[92:95], v[164:167], v[180:183], v[92:95]
	v_mfma_f32_16x16x32_bf16 v[84:87], v[156:159], v[196:199], v[84:87]
	v_mfma_f32_16x16x32_bf16 v[76:79], v[164:167], v[196:199], v[76:79]
	v_mfma_f32_16x16x32_bf16 v[68:71], v[156:159], v[204:207], v[68:71]
	v_mfma_f32_16x16x32_bf16 v[64:67], v[164:167], v[204:207], v[64:67]
	v_mfma_f32_16x16x32_bf16 v[116:119], v[160:163], v[176:179], v[116:119]
	v_mfma_f32_16x16x32_bf16 v[108:111], v[168:171], v[176:179], v[108:111]
	v_mfma_f32_16x16x32_bf16 v[100:103], v[160:163], v[184:187], v[100:103]
	v_mfma_f32_16x16x32_bf16 v[92:95], v[168:171], v[184:187], v[92:95]
	v_mfma_f32_16x16x32_bf16 v[84:87], v[160:163], v[200:203], v[84:87]
	v_mfma_f32_16x16x32_bf16 v[76:79], v[168:171], v[200:203], v[76:79]
	v_mfma_f32_16x16x32_bf16 v[68:71], v[160:163], v[208:211], v[68:71]
	v_mfma_f32_16x16x32_bf16 v[64:67], v[168:171], v[208:211], v[64:67]
	s_barrier
	s_setprio 0
	s_add_i32 s42, s33, s23
	s_mov_b32 m0, s42
	s_nop 0
	global_load_lds_dwordx4 v128, s[16:17]
	s_add_i32 m0, s42, 0x2000
	s_add_u32 s42, s16, 0x2b0000
	s_addc_u32 s43, s17, 0
	s_add_i32 s44, s34, s23
	global_load_lds_dwordx4 v130, s[16:17]
	s_mov_b32 m0, s44
	s_nop 0
	global_load_lds_dwordx4 v128, s[42:43]
	s_add_i32 m0, s44, 0x2000
	s_nop 0
	global_load_lds_dwordx4 v130, s[42:43]
	ds_read_b128 v[172:175], v195 offset:16384
	ds_read_b128 v[176:179], v195 offset:17408
	ds_read_b128 v[180:183], v195 offset:18432
	ds_read_b128 v[184:187], v195 offset:19456
	ds_read_b128 v[196:199], v195 offset:20480
	ds_read_b128 v[200:203], v195 offset:21504
	ds_read_b128 v[204:207], v195 offset:22528
	ds_read_b128 v[208:211], v195 offset:23552
	s_waitcnt vmcnt(6)
	s_waitcnt lgkmcnt(0)
	s_setprio 1
	s_barrier
	v_mfma_f32_16x16x32_bf16 v[60:63], v[140:143], v[172:175], v[60:63]
	v_mfma_f32_16x16x32_bf16 v[56:59], v[148:151], v[172:175], v[56:59]
	v_mfma_f32_16x16x32_bf16 v[48:51], v[140:143], v[180:183], v[48:51]
	v_mfma_f32_16x16x32_bf16 v[40:43], v[148:151], v[180:183], v[40:43]
	v_mfma_f32_16x16x32_bf16 v[32:35], v[140:143], v[196:199], v[32:35]
	v_mfma_f32_16x16x32_bf16 v[24:27], v[148:151], v[196:199], v[24:27]
	v_mfma_f32_16x16x32_bf16 v[16:19], v[140:143], v[204:207], v[16:19]
	v_mfma_f32_16x16x32_bf16 v[8:11], v[148:151], v[204:207], v[8:11]
	v_mfma_f32_16x16x32_bf16 v[60:63], v[144:147], v[176:179], v[60:63]
	v_mfma_f32_16x16x32_bf16 v[56:59], v[152:155], v[176:179], v[56:59]
	v_mfma_f32_16x16x32_bf16 v[48:51], v[144:147], v[184:187], v[48:51]
	v_mfma_f32_16x16x32_bf16 v[40:43], v[152:155], v[184:187], v[40:43]
	v_mfma_f32_16x16x32_bf16 v[32:35], v[144:147], v[200:203], v[32:35]
	v_mfma_f32_16x16x32_bf16 v[24:27], v[152:155], v[200:203], v[24:27]
	v_mfma_f32_16x16x32_bf16 v[16:19], v[144:147], v[208:211], v[16:19]
	v_mfma_f32_16x16x32_bf16 v[8:11], v[152:155], v[208:211], v[8:11]
	v_mfma_f32_16x16x32_bf16 v[52:55], v[156:159], v[172:175], v[52:55]
	v_mfma_f32_16x16x32_bf16 v[44:47], v[164:167], v[172:175], v[44:47]
	v_mfma_f32_16x16x32_bf16 v[36:39], v[156:159], v[180:183], v[36:39]
	v_mfma_f32_16x16x32_bf16 v[28:31], v[164:167], v[180:183], v[28:31]
	v_mfma_f32_16x16x32_bf16 v[20:23], v[156:159], v[196:199], v[20:23]
	v_mfma_f32_16x16x32_bf16 v[12:15], v[164:167], v[196:199], v[12:15]
	v_mfma_f32_16x16x32_bf16 v[4:7], v[156:159], v[204:207], v[4:7]
	v_mfma_f32_16x16x32_bf16 v[0:3], v[164:167], v[204:207], v[0:3]
	v_mfma_f32_16x16x32_bf16 v[52:55], v[160:163], v[176:179], v[52:55]
	v_mfma_f32_16x16x32_bf16 v[44:47], v[168:171], v[176:179], v[44:47]
	v_mfma_f32_16x16x32_bf16 v[36:39], v[160:163], v[184:187], v[36:39]
	v_mfma_f32_16x16x32_bf16 v[28:31], v[168:171], v[184:187], v[28:31]
	v_mfma_f32_16x16x32_bf16 v[20:23], v[160:163], v[200:203], v[20:23]
	v_mfma_f32_16x16x32_bf16 v[12:15], v[168:171], v[200:203], v[12:15]
	v_mfma_f32_16x16x32_bf16 v[4:7], v[160:163], v[208:211], v[4:7]
	v_mfma_f32_16x16x32_bf16 v[0:3], v[168:171], v[208:211], v[0:3]
	s_barrier
; #define PG8_STAGE(bufoff, gbase, voff) do { _Pragma("unroll") for (int _i = 0; _i < 2; ++_i) \
;         __builtin_amdgcn_global_load_lds((const unsigned*)((const char*)(gbase) + (voff)[_i]), (PG8_LAS unsigned*)(lds + (bufoff) + ldsw + _i * 8192), 16, 0, 0); } while (0)
; #define PG8_LDA(dst, b, h) do { _Pragma("unroll") for (int m = 0; m < 4; ++m) _Pragma("unroll") for (int k = 0; k < 2; ++k) dst[m][k] = *(const PG8_LAS bf16x8*)(lds + PG8_SA(b, h) + aoff + m * 2048 + k * 1024); } while (0)
; #define PG8_LDB(dst, b, h) do { _Pragma("unroll") for (int n = 0; n < 2; ++n) _Pragma("unroll") for (int k = 0; k < 2; ++k) dst[n][k] = *(const PG8_LAS bf16x8*)(lds + PG8_SB(b, h) + boff + n * 2048 + k * 1024); } while (0)
; #define PG8_MMA(ai, bj, At, Bt) do { __builtin_amdgcn_s_setprio(1); _Pragma("unroll") for (int m = 0; m < 4; ++m) _Pragma("unroll") for (int n = 0; n < 2; ++n) _Pragma("unroll") for (int k = 0; k < 2; ++k) \
;         acc[ai][bj][m][n] = __builtin_amdgcn_mfma_f32_16x16x32_bf16(Bt[n][k], At[m][k], acc[ai][bj][m][n], 0, 0, 0); __builtin_amdgcn_s_setprio(0); } while (0)
; #define PG8_WAIT_V(n) asm volatile("s_waitcnt vmcnt(" #n ")" ::: "memory")
; #define PG8_WAIT_L(n) asm volatile("s_waitcnt lgkmcnt(" #n ")" ::: "memory")
; #define PG8_BAR __builtin_amdgcn_s_barrier()
; #define PG8_SCHED __builtin_amdgcn_sched_barrier(0)
; template <class Epi, class Sched, bool ALIGN_EPI = false, bool SP2 = false>
; __device__ __forceinline__ void gemm_phase(PG8_LAS unsigned char* lds, const Gemm g, const Sched& S, const Epi& E) {
;     ...
;             PG8_LDB(B0, 1, 0); PG8_LDB(B1, 1, 1); PG8_SCHED; PG8_LDA(At, 1, 0); PG8_STAGE(PG8_SA(0, 1), a2 + hstep, voffA);
;             PG8_WAIT_V(8); PG8_WAIT_L(0); PG8_BAR; PG8_MMA(0, 0, At, B0); PG8_MMA(0, 1, At, B1); PG8_BAR; PG8_SCHED;
;             PG8_LDA(At, 1, 1); PG8_STAGE(PG8_SB(1, 0), b3, voffB); PG8_STAGE(PG8_SB(1, 1), b3 + hstep, voffB); PG8_STAGE(PG8_SA(1, 0), a3, voffA);
;             PG8_WAIT_V(8); PG8_WAIT_L(0); PG8_BAR; PG8_MMA(1, 0, At, B0); PG8_MMA(1, 1, At, B1); PG8_BAR; PG8_SCHED;
	s_setprio 0
	s_mov_b32 m0, s24
	s_nop 0
	global_load_lds_dwordx4 v128, s[20:21]
	s_mov_b32 m0, s25
	s_nop 0
	global_load_lds_dwordx4 v130, s[20:21]
	s_add_i32 s42, 0, 0x18000
	s_add_i32 s43, 0, 0x1c000
	s_add_u32 s20, s20, 0x2b0000
	s_addc_u32 s21, s21, 0
	s_mov_b32 m0, s26
	s_nop 0
	global_load_lds_dwordx4 v128, s[20:21]
	s_mov_b32 m0, s27
	s_nop 0
	global_load_lds_dwordx4 v130, s[20:21]
	v_add_u32_e32 v152, s42, v191
	v_add_u32_e32 v168, s43, v191
	ds_read_b128 v[140:143], v152
	ds_read_b128 v[144:147], v152 offset:1024
	ds_read_b128 v[148:151], v152 offset:2048
	ds_read_b128 v[152:155], v152 offset:3072
	ds_read_b128 v[156:159], v168
	ds_read_b128 v[160:163], v168 offset:1024
	ds_read_b128 v[164:167], v168 offset:2048
	ds_read_b128 v[168:171], v168 offset:3072
	ds_read_b128 v[172:175], v195 offset:32768
	ds_read_b128 v[176:179], v195 offset:33792
	ds_read_b128 v[180:183], v195 offset:34816
	ds_read_b128 v[184:187], v195 offset:35840
	ds_read_b128 v[196:199], v195 offset:36864
	ds_read_b128 v[200:203], v195 offset:37888
	ds_read_b128 v[204:207], v195 offset:38912
	ds_read_b128 v[208:211], v195 offset:39936
	s_waitcnt vmcnt(8)
	s_waitcnt lgkmcnt(0)
	s_setprio 1
	s_barrier
	v_mfma_f32_16x16x32_bf16 v[124:127], v[140:143], v[172:175], v[124:127]
	v_mfma_f32_16x16x32_bf16 v[120:123], v[148:151], v[172:175], v[120:123]
	v_mfma_f32_16x16x32_bf16 v[112:115], v[140:143], v[180:183], v[112:115]
	v_mfma_f32_16x16x32_bf16 v[104:107], v[148:151], v[180:183], v[104:107]
	v_mfma_f32_16x16x32_bf16 v[96:99], v[140:143], v[196:199], v[96:99]
	v_mfma_f32_16x16x32_bf16 v[88:91], v[148:151], v[196:199], v[88:91]
	v_mfma_f32_16x16x32_bf16 v[80:83], v[140:143], v[204:207], v[80:83]
	v_mfma_f32_16x16x32_bf16 v[72:75], v[148:151], v[204:207], v[72:75]
	v_mfma_f32_16x16x32_bf16 v[124:127], v[144:147], v[176:179], v[124:127]
	v_mfma_f32_16x16x32_bf16 v[120:123], v[152:155], v[176:179], v[120:123]
	v_mfma_f32_16x16x32_bf16 v[112:115], v[144:147], v[184:187], v[112:115]
	v_mfma_f32_16x16x32_bf16 v[104:107], v[152:155], v[184:187], v[104:107]
	v_mfma_f32_16x16x32_bf16 v[96:99], v[144:147], v[200:203], v[96:99]
	v_mfma_f32_16x16x32_bf16 v[88:91], v[152:155], v[200:203], v[88:91]
	v_mfma_f32_16x16x32_bf16 v[80:83], v[144:147], v[208:211], v[80:83]
	v_mfma_f32_16x16x32_bf16 v[72:75], v[152:155], v[208:211], v[72:75]
	v_mfma_f32_16x16x32_bf16 v[116:119], v[156:159], v[172:175], v[116:119]
	v_mfma_f32_16x16x32_bf16 v[108:111], v[164:167], v[172:175], v[108:111]
	v_mfma_f32_16x16x32_bf16 v[100:103], v[156:159], v[180:183], v[100:103]
	v_mfma_f32_16x16x32_bf16 v[92:95], v[164:167], v[180:183], v[92:95]
	v_mfma_f32_16x16x32_bf16 v[84:87], v[156:159], v[196:199], v[84:87]
	v_mfma_f32_16x16x32_bf16 v[76:79], v[164:167], v[196:199], v[76:79]
	v_mfma_f32_16x16x32_bf16 v[68:71], v[156:159], v[204:207], v[68:71]
	v_mfma_f32_16x16x32_bf16 v[64:67], v[164:167], v[204:207], v[64:67]
	v_mfma_f32_16x16x32_bf16 v[116:119], v[160:163], v[176:179], v[116:119]
	v_mfma_f32_16x16x32_bf16 v[108:111], v[168:171], v[176:179], v[108:111]
	v_mfma_f32_16x16x32_bf16 v[100:103], v[160:163], v[184:187], v[100:103]
	v_mfma_f32_16x16x32_bf16 v[92:95], v[168:171], v[184:187], v[92:95]
	v_mfma_f32_16x16x32_bf16 v[84:87], v[160:163], v[200:203], v[84:87]
	v_mfma_f32_16x16x32_bf16 v[76:79], v[168:171], v[200:203], v[76:79]
	v_mfma_f32_16x16x32_bf16 v[68:71], v[160:163], v[208:211], v[68:71]
	v_mfma_f32_16x16x32_bf16 v[64:67], v[168:171], v[208:211], v[64:67]
	s_barrier
	s_setprio 0
	s_add_i32 s20, s42, s23
	s_add_u32 s16, s16, 0x80
	s_addc_u32 s17, s17, 0
	s_mov_b32 m0, s20
	s_nop 0
	global_load_lds_dwordx4 v128, s[16:17]
	s_add_i32 m0, s20, 0x2000
	s_add_i32 s20, s43, s23
	global_load_lds_dwordx4 v130, s[16:17]
	s_add_u32 s16, s16, 0x2b0000
	s_addc_u32 s17, s17, 0
	s_mov_b32 m0, s20
	s_nop 0
	global_load_lds_dwordx4 v128, s[16:17]
	s_add_i32 m0, s20, 0x2000
	s_nop 0
	global_load_lds_dwordx4 v130, s[16:17]
	ds_read_b128 v[172:175], v195 offset:49152
	ds_read_b128 v[176:179], v195 offset:50176
	ds_read_b128 v[180:183], v195 offset:51200
	ds_read_b128 v[184:187], v195 offset:52224
	ds_read_b128 v[196:199], v195 offset:53248
	ds_read_b128 v[200:203], v195 offset:54272
	ds_read_b128 v[204:207], v195 offset:55296
	ds_read_b128 v[208:211], v195 offset:56320
	s_waitcnt vmcnt(6)
	s_waitcnt lgkmcnt(0)
	s_setprio 1
	s_barrier
	v_mfma_f32_16x16x32_bf16 v[60:63], v[140:143], v[172:175], v[60:63]
	v_mfma_f32_16x16x32_bf16 v[56:59], v[148:151], v[172:175], v[56:59]
	v_mfma_f32_16x16x32_bf16 v[48:51], v[140:143], v[180:183], v[48:51]
	v_mfma_f32_16x16x32_bf16 v[40:43], v[148:151], v[180:183], v[40:43]
	v_mfma_f32_16x16x32_bf16 v[32:35], v[140:143], v[196:199], v[32:35]
	v_mfma_f32_16x16x32_bf16 v[24:27], v[148:151], v[196:199], v[24:27]
	v_mfma_f32_16x16x32_bf16 v[16:19], v[140:143], v[204:207], v[16:19]
	v_mfma_f32_16x16x32_bf16 v[8:11], v[148:151], v[204:207], v[8:11]
	v_mfma_f32_16x16x32_bf16 v[60:63], v[144:147], v[176:179], v[60:63]
	v_mfma_f32_16x16x32_bf16 v[56:59], v[152:155], v[176:179], v[56:59]
	v_mfma_f32_16x16x32_bf16 v[48:51], v[144:147], v[184:187], v[48:51]
	v_mfma_f32_16x16x32_bf16 v[40:43], v[152:155], v[184:187], v[40:43]
	v_mfma_f32_16x16x32_bf16 v[32:35], v[144:147], v[200:203], v[32:35]
	v_mfma_f32_16x16x32_bf16 v[24:27], v[152:155], v[200:203], v[24:27]
	v_mfma_f32_16x16x32_bf16 v[16:19], v[144:147], v[208:211], v[16:19]
	v_mfma_f32_16x16x32_bf16 v[8:11], v[152:155], v[208:211], v[8:11]
	v_mfma_f32_16x16x32_bf16 v[52:55], v[156:159], v[172:175], v[52:55]
	v_mfma_f32_16x16x32_bf16 v[44:47], v[164:167], v[172:175], v[44:47]
	v_mfma_f32_16x16x32_bf16 v[36:39], v[156:159], v[180:183], v[36:39]
	v_mfma_f32_16x16x32_bf16 v[28:31], v[164:167], v[180:183], v[28:31]
	v_mfma_f32_16x16x32_bf16 v[20:23], v[156:159], v[196:199], v[20:23]
	v_mfma_f32_16x16x32_bf16 v[12:15], v[164:167], v[196:199], v[12:15]
	v_mfma_f32_16x16x32_bf16 v[4:7], v[156:159], v[204:207], v[4:7]
	v_mfma_f32_16x16x32_bf16 v[0:3], v[164:167], v[204:207], v[0:3]
	v_mfma_f32_16x16x32_bf16 v[52:55], v[160:163], v[176:179], v[52:55]
	v_mfma_f32_16x16x32_bf16 v[44:47], v[168:171], v[176:179], v[44:47]
	v_mfma_f32_16x16x32_bf16 v[36:39], v[160:163], v[184:187], v[36:39]
	v_mfma_f32_16x16x32_bf16 v[28:31], v[168:171], v[184:187], v[28:31]
	v_mfma_f32_16x16x32_bf16 v[20:23], v[160:163], v[200:203], v[20:23]
	v_mfma_f32_16x16x32_bf16 v[12:15], v[168:171], v[200:203], v[12:15]
	v_mfma_f32_16x16x32_bf16 v[4:7], v[160:163], v[208:211], v[4:7]
	v_mfma_f32_16x16x32_bf16 v[0:3], v[168:171], v[208:211], v[0:3]
	s_barrier
	s_setprio 0
	s_add_i32 s41, s41, 2
	s_add_u32 s14, s14, 0x100
	s_addc_u32 s15, s15, 0
	s_add_u32 s39, s39, 0x100
	s_addc_u32 s40, s40, 0
	s_cmpk_gt_u32 s41, 0xa9
	s_cbranch_scc0 .LBB0_1164
	s_and_b64 vcc, exec, s[10:11]
	s_cbranch_vccz .LBB0_1167
	s_barrier
